# packed-f32 ConvFFN epilogue body + packed WIN gate epilogue + v_pk_mov accumulator zeroing
# speedup vs baseline: 1.0116x; 1.0030x over previous
.LBB0_309:
	s_mul_i32 s3, s74, 0x8400
	v_readlane_b32 s48, v252, 45
	s_ashr_i32 s4, s3, 31
	v_readlane_b32 s60, v252, 57
	v_readlane_b32 s61, v252, 58
	s_add_u32 s30, s60, s3
	s_addc_u32 s31, s61, s4
	s_mov_b64 s[4:5], 0x80
	v_readlane_b32 s50, v252, 47
	s_lshl_b32 s1, s1, 5
	v_lshl_add_u64 v[8:9], v[8:9], 0, s[4:5]
	s_add_i32 m0, s15, 0x18000
	v_readlane_b32 s51, v252, 48
	s_and_b32 s44, s1, 0x60
	s_waitcnt vmcnt(2)
	s_barrier
	global_load_lds_dwordx4 v[8:9], off
	v_lshl_add_u64 v[6:7], v[6:7], 0, s[4:5]
	s_add_i32 m0, s15, 0x1a000
	s_add_i32 s50, s15, 0x8000
	s_lshl_b32 s41, s0, 6
	s_lshl_b32 s3, s0, 13
	s_lshl_b32 s1, s44, 7
	global_load_lds_dwordx4 v[6:7], off
	v_lshl_add_u64 v[2:3], v[2:3], 0, s[4:5]
	s_mov_b32 m0, s50
	s_add_i32 s51, s15, 0xa000
	global_load_lds_dwordx4 v[2:3], off
	v_lshl_add_u64 v[2:3], v[4:5], 0, s[4:5]
	s_add_u32 s4, s26, 0x40080
	s_mov_b32 m0, s51
	s_addc_u32 s5, s27, 0
	global_load_lds_dwordx4 v[2:3], off
	v_lshl_add_u64 v[2:3], s[4:5], 0, v[170:171]
	s_add_i32 m0, s15, 0x1c000
	v_bfe_u32 v189, v10, 4, 2
	global_load_lds_dwordx4 v[2:3], off
	v_lshl_add_u64 v[2:3], s[4:5], 0, v[172:173]
	s_add_i32 m0, s15, 0x1e000
	v_and_b32_e32 v188, 15, v10
	global_load_lds_dwordx4 v[2:3], off
	v_lshlrev_b32_e32 v13, 4, v189
	v_lshlrev_b32_e32 v10, 2, v10
	v_lshl_or_b32 v13, v188, 6, v13
	v_and_b32_e32 v10, 32, v10
	s_cmpk_lt_u32 s2, 0x100
	v_bitop3_b32 v190, v13, s1, v10 bitop3:0xde
	s_cselect_b64 s[36:37], -1, 0
	s_lshl_b32 s1, s0, 10
	s_cmp_gt_i32 s0, 0
	s_cselect_b64 s[38:39], -1, 0
	s_cmp_gt_i32 s0, -2
	s_mul_i32 s0, s74, 0x2600000
	s_cselect_b64 s[46:47], -1, 0
	s_ashr_i32 s2, s0, 31
	s_add_u32 s0, s82, s0
	v_readlane_b32 s62, v252, 59
	s_addc_u32 s2, s83, s2
	v_readlane_b32 s63, v252, 60
	s_add_u32 s62, s0, 0x1680000
	v_bitop3_b32 v14, v13, s3, v10 bitop3:0xde
	s_addc_u32 s63, s2, 0
	v_readlane_b32 s2, v253, 25
	s_mov_b32 s4, s2
	s_mul_hi_i32 s0, s2, 0x180000
	s_mul_i32 s2, s2, 0x180000
	v_readlane_b32 s3, v253, 26
	s_add_u32 s2, s82, s2
	s_addc_u32 s0, s83, s0
	s_mul_hi_i32 s3, s4, 0xffea0000
	s_mul_i32 s4, s4, 0xffea0000
	s_add_u32 s2, s2, s4
	s_addc_u32 s0, s0, s3
	s_add_u32 s64, s2, 0x15000000
	s_addc_u32 s65, s0, 0
	v_lshlrev_b32_e32 v2, 14, v0
	v_readlane_b32 s49, v252, 46
	s_add_u32 s48, s82, 0x1f000000
	v_and_b32_e32 v2, 0xffff8000, v2
	s_addc_u32 s49, s83, 0
	v_and_b32_e32 v0, 1, v0
	v_lshl_add_u32 v2, v11, 11, v2
	s_waitcnt vmcnt(6)
	s_add_u32 s10, s82, 0x1f160000
	v_lshl_or_b32 v0, v0, 6, v2
	s_addc_u32 s11, s83, 0
	s_add_i32 s67, s1, 0
	v_lshl_add_u32 v178, v12, 1, v0
	v_pk_mov_b32 v[2:3], 0, 0
	v_readlane_b32 s52, v252, 49
	v_readlane_b32 s53, v252, 50
	v_readlane_b32 s54, v252, 51
	s_mov_b32 s69, 0
	s_add_i32 s66, s67, 0x21c00
	s_add_i32 s67, s67, 0x21800
	v_add_u32_e32 v180, 0x20000, v178
	v_mov_b32_e32 v181, v1
	v_mov_b32_e32 v179, v1
	v_add_u32_e32 v191, 0, v14
	v_pk_mov_b32 v[4:5], 0, 0
	v_pk_mov_b32 v[6:7], 0, 0
	v_pk_mov_b32 v[8:9], 0, 0
	v_pk_mov_b32 v[10:11], 0, 0
	v_pk_mov_b32 v[12:13], 0, 0
	v_pk_mov_b32 v[14:15], 0, 0
	v_pk_mov_b32 v[16:17], 0, 0
	v_pk_mov_b32 v[18:19], 0, 0
	v_pk_mov_b32 v[20:21], 0, 0
	v_pk_mov_b32 v[22:23], 0, 0
	v_pk_mov_b32 v[24:25], 0, 0
	v_pk_mov_b32 v[26:27], 0, 0
	v_pk_mov_b32 v[28:29], 0, 0
	v_pk_mov_b32 v[30:31], 0, 0
	v_pk_mov_b32 v[32:33], 0, 0
	v_pk_mov_b32 v[34:35], 0, 0
	v_pk_mov_b32 v[36:37], 0, 0
	v_pk_mov_b32 v[38:39], 0, 0
	v_pk_mov_b32 v[40:41], 0, 0
	v_pk_mov_b32 v[42:43], 0, 0
	v_pk_mov_b32 v[44:45], 0, 0
	v_pk_mov_b32 v[46:47], 0, 0
	v_pk_mov_b32 v[48:49], 0, 0
	v_pk_mov_b32 v[50:51], 0, 0
	v_pk_mov_b32 v[52:53], 0, 0
	v_pk_mov_b32 v[54:55], 0, 0
	v_pk_mov_b32 v[56:57], 0, 0
	v_pk_mov_b32 v[58:59], 0, 0
	v_pk_mov_b32 v[60:61], 0, 0
	v_pk_mov_b32 v[62:63], 0, 0
	v_pk_mov_b32 v[64:65], 0, 0
	v_pk_mov_b32 v[66:67], 0, 0
	v_pk_mov_b32 v[68:69], 0, 0
	v_pk_mov_b32 v[70:71], 0, 0
	v_pk_mov_b32 v[72:73], 0, 0
	v_pk_mov_b32 v[74:75], 0, 0
	v_pk_mov_b32 v[76:77], 0, 0
	v_pk_mov_b32 v[78:79], 0, 0
	v_pk_mov_b32 v[80:81], 0, 0
	v_pk_mov_b32 v[82:83], 0, 0
	v_pk_mov_b32 v[84:85], 0, 0
	v_pk_mov_b32 v[86:87], 0, 0
	v_pk_mov_b32 v[88:89], 0, 0
	v_pk_mov_b32 v[90:91], 0, 0
	v_pk_mov_b32 v[92:93], 0, 0
	v_pk_mov_b32 v[94:95], 0, 0
	v_pk_mov_b32 v[96:97], 0, 0
	v_pk_mov_b32 v[98:99], 0, 0
	v_pk_mov_b32 v[100:101], 0, 0
	v_pk_mov_b32 v[102:103], 0, 0
	v_pk_mov_b32 v[104:105], 0, 0
	v_pk_mov_b32 v[106:107], 0, 0
	v_pk_mov_b32 v[108:109], 0, 0
	v_pk_mov_b32 v[110:111], 0, 0
	v_pk_mov_b32 v[112:113], 0, 0
	v_pk_mov_b32 v[114:115], 0, 0
	v_pk_mov_b32 v[116:117], 0, 0
	v_pk_mov_b32 v[118:119], 0, 0
	v_pk_mov_b32 v[120:121], 0, 0
	v_pk_mov_b32 v[122:123], 0, 0
	v_pk_mov_b32 v[124:125], 0, 0
	v_pk_mov_b32 v[126:127], 0, 0
	v_pk_mov_b32 v[128:129], 0, 0
	v_readlane_b32 s55, v252, 52
	v_readlane_b32 s56, v252, 53
	v_readlane_b32 s57, v252, 54
	v_readlane_b32 s58, v252, 55
	v_readlane_b32 s59, v252, 56
	s_barrier
	s_branch .LBB0_314

.LBB0_313:
	v_pk_mov_b32 v[2:3], 0, 0
	v_pk_mov_b32 v[4:5], 0, 0
	v_pk_mov_b32 v[6:7], 0, 0
	v_pk_mov_b32 v[8:9], 0, 0
	v_pk_mov_b32 v[10:11], 0, 0
	v_pk_mov_b32 v[12:13], 0, 0
	v_pk_mov_b32 v[14:15], 0, 0
	v_pk_mov_b32 v[16:17], 0, 0
	v_pk_mov_b32 v[18:19], 0, 0
	v_pk_mov_b32 v[20:21], 0, 0
	v_pk_mov_b32 v[22:23], 0, 0
	v_pk_mov_b32 v[24:25], 0, 0
	v_pk_mov_b32 v[26:27], 0, 0
	v_pk_mov_b32 v[28:29], 0, 0
	v_pk_mov_b32 v[30:31], 0, 0
	v_pk_mov_b32 v[32:33], 0, 0
	v_pk_mov_b32 v[34:35], 0, 0
	v_pk_mov_b32 v[36:37], 0, 0
	v_pk_mov_b32 v[38:39], 0, 0
	v_pk_mov_b32 v[40:41], 0, 0
	v_pk_mov_b32 v[42:43], 0, 0
	v_pk_mov_b32 v[44:45], 0, 0
	v_pk_mov_b32 v[46:47], 0, 0
	v_pk_mov_b32 v[48:49], 0, 0
	v_pk_mov_b32 v[50:51], 0, 0
	v_pk_mov_b32 v[52:53], 0, 0
	v_pk_mov_b32 v[54:55], 0, 0
	v_pk_mov_b32 v[56:57], 0, 0
	v_pk_mov_b32 v[58:59], 0, 0
	v_pk_mov_b32 v[60:61], 0, 0
	v_pk_mov_b32 v[62:63], 0, 0
	v_pk_mov_b32 v[64:65], 0, 0
	v_pk_mov_b32 v[66:67], 0, 0
	v_pk_mov_b32 v[68:69], 0, 0
	v_pk_mov_b32 v[70:71], 0, 0
	v_pk_mov_b32 v[72:73], 0, 0
	v_pk_mov_b32 v[74:75], 0, 0
	v_pk_mov_b32 v[76:77], 0, 0
	v_pk_mov_b32 v[78:79], 0, 0
	v_pk_mov_b32 v[80:81], 0, 0
	v_pk_mov_b32 v[82:83], 0, 0
	v_pk_mov_b32 v[84:85], 0, 0
	v_pk_mov_b32 v[86:87], 0, 0
	v_pk_mov_b32 v[88:89], 0, 0
	v_pk_mov_b32 v[90:91], 0, 0
	v_pk_mov_b32 v[92:93], 0, 0
	v_pk_mov_b32 v[94:95], 0, 0
	v_pk_mov_b32 v[96:97], 0, 0
	v_pk_mov_b32 v[98:99], 0, 0
	v_pk_mov_b32 v[100:101], 0, 0
	v_pk_mov_b32 v[102:103], 0, 0
	v_pk_mov_b32 v[104:105], 0, 0
	v_pk_mov_b32 v[106:107], 0, 0
	v_pk_mov_b32 v[108:109], 0, 0
	v_pk_mov_b32 v[110:111], 0, 0
	v_pk_mov_b32 v[112:113], 0, 0
	v_pk_mov_b32 v[114:115], 0, 0
	v_pk_mov_b32 v[116:117], 0, 0
	v_pk_mov_b32 v[118:119], 0, 0
	v_pk_mov_b32 v[120:121], 0, 0
	v_pk_mov_b32 v[122:123], 0, 0
	v_pk_mov_b32 v[124:125], 0, 0
	v_pk_mov_b32 v[126:127], 0, 0
	v_pk_mov_b32 v[128:129], 0, 0
	s_mov_b64 s[34:35], s[58:59]
	s_mov_b32 s69, s70
	s_andn2_b64 vcc, exec, s[56:57]
	s_cbranch_vccz .LBB0_338

.Lffn_d0:
	v_add_u32_e32 v230, s41, v184
	s_lshl_b32 s6, s54, 8
	v_add_u32_e32 v230, s6, v230
	v_mov_b64_e32 v[158:159], s[52:53]
	s_movk_i32 s6, 0x1600
	v_mad_i64_i32 v[158:159], s[8:9], v230, s6, v[158:159]
	v_lshl_add_u64 v[158:159], v[182:183], 1, v[158:159]
	v_lshl_add_u64 v[158:159], v[186:187], 1, v[158:159]
	s_mov_b32 s6, 0x16000
	s_mov_b32 s7, 0
	s_mov_b32 s2, 0xbfb8aa3b
	s_mov_b32 s3, 1.0
	v_cmp_eq_u32_e64 s[4:5], 0, v184
	v_cmp_lt_i32_e64 s[0:1], 0, v184
	v_cmp_lt_i32_e64 s[8:9], 1, v184
	s_waitcnt vmcnt(0) lgkmcnt(0)
	v_cndmask_b32_e64 v200, v192, v200, s[4:5]
	v_cndmask_b32_e64 v201, v193, v201, s[4:5]
	v_cndmask_b32_e64 v202, v194, v202, s[4:5]
	v_cndmask_b32_e64 v203, v195, v203, s[4:5]
	v_cndmask_b32_e64 v204, v196, v204, s[4:5]
	v_cndmask_b32_e64 v205, v197, v205, s[4:5]
	v_cndmask_b32_e64 v206, v198, v206, s[4:5]
	v_cndmask_b32_e64 v207, v199, v207, s[4:5]
	v_mov_b32_dpp v208, v126 row_ror:1 row_mask:0xf bank_mask:0xf
	v_mov_b32_dpp v209, v127 row_ror:1 row_mask:0xf bank_mask:0xf
	v_mov_b32_dpp v210, v128 row_ror:1 row_mask:0xf bank_mask:0xf
	v_mov_b32_dpp v211, v129 row_ror:1 row_mask:0xf bank_mask:0xf
	v_mov_b32_dpp v212, v122 row_ror:1 row_mask:0xf bank_mask:0xf
	v_mov_b32_dpp v213, v123 row_ror:1 row_mask:0xf bank_mask:0xf
	v_mov_b32_dpp v214, v124 row_ror:1 row_mask:0xf bank_mask:0xf
	v_mov_b32_dpp v215, v125 row_ror:1 row_mask:0xf bank_mask:0xf
	v_mov_b32_dpp v160, v126 row_ror:2 row_mask:0xf bank_mask:0xf
	v_mov_b32_dpp v161, v127 row_ror:2 row_mask:0xf bank_mask:0xf
	v_mov_b32_dpp v162, v128 row_ror:2 row_mask:0xf bank_mask:0xf
	v_mov_b32_dpp v163, v129 row_ror:2 row_mask:0xf bank_mask:0xf
	v_mov_b32_dpp v164, v122 row_ror:2 row_mask:0xf bank_mask:0xf
	v_mov_b32_dpp v165, v123 row_ror:2 row_mask:0xf bank_mask:0xf
	v_mov_b32_dpp v166, v124 row_ror:2 row_mask:0xf bank_mask:0xf
	v_mov_b32_dpp v167, v125 row_ror:2 row_mask:0xf bank_mask:0xf
	v_cndmask_b32_e64 v192, v192, v208, s[0:1]
	v_cndmask_b32_e64 v193, v193, v209, s[0:1]
	v_cndmask_b32_e64 v194, v194, v210, s[0:1]
	v_cndmask_b32_e64 v195, v195, v211, s[0:1]
	v_cndmask_b32_e64 v196, v196, v212, s[0:1]
	v_cndmask_b32_e64 v197, v197, v213, s[0:1]
	v_cndmask_b32_e64 v198, v198, v214, s[0:1]
	v_cndmask_b32_e64 v199, v199, v215, s[0:1]
	v_cndmask_b32_e64 v200, v200, v160, s[8:9]
	v_cndmask_b32_e64 v201, v201, v161, s[8:9]
	v_cndmask_b32_e64 v202, v202, v162, s[8:9]
	v_cndmask_b32_e64 v203, v203, v163, s[8:9]
	v_cndmask_b32_e64 v204, v204, v164, s[8:9]
	v_cndmask_b32_e64 v205, v205, v165, s[8:9]
	v_cndmask_b32_e64 v206, v206, v166, s[8:9]
	v_cndmask_b32_e64 v207, v207, v167, s[8:9]
	v_pk_mul_f32 v[192:193], v[146:147], v[192:193]
	v_pk_mul_f32 v[194:195], v[148:149], v[194:195]
	v_pk_mul_f32 v[196:197], v[134:135], v[196:197]
	v_pk_mul_f32 v[198:199], v[136:137], v[198:199]
	v_pk_mul_f32 v[168:169], v[126:127], v[150:151]
	v_pk_mul_f32 v[182:183], v[128:129], v[152:153]
	v_pk_mul_f32 v[184:185], v[122:123], v[138:139]
	v_pk_mul_f32 v[186:187], v[124:125], v[140:141]
	v_pk_fma_f32 v[200:201], v[142:143], v[200:201], v[192:193]
	v_pk_fma_f32 v[202:203], v[144:145], v[202:203], v[194:195]
	v_pk_fma_f32 v[204:205], v[130:131], v[204:205], v[196:197]
	v_pk_fma_f32 v[206:207], v[132:133], v[206:207], v[198:199]
	v_pk_add_f32 v[168:169], v[168:169], v[200:201]
	v_pk_add_f32 v[182:183], v[182:183], v[202:203]
	v_pk_add_f32 v[184:185], v[184:185], v[204:205]
	v_pk_add_f32 v[186:187], v[186:187], v[206:207]
	v_pk_mul_f32 v[200:201], v[168:169], s[2:3] op_sel_hi:[1,0]
	v_pk_mul_f32 v[202:203], v[182:183], s[2:3] op_sel_hi:[1,0]
	v_pk_mul_f32 v[204:205], v[184:185], s[2:3] op_sel_hi:[1,0]
	v_pk_mul_f32 v[206:207], v[186:187], s[2:3] op_sel_hi:[1,0]
	v_exp_f32_e32 v200, v200
	v_exp_f32_e32 v201, v201
	v_exp_f32_e32 v202, v202
	v_exp_f32_e32 v203, v203
	v_exp_f32_e32 v204, v204
	v_exp_f32_e32 v205, v205
	v_exp_f32_e32 v206, v206
	v_exp_f32_e32 v207, v207
	v_pk_add_f32 v[200:201], v[200:201], s[2:3] op_sel:[0,1] op_sel_hi:[1,1]
	v_pk_add_f32 v[202:203], v[202:203], s[2:3] op_sel:[0,1] op_sel_hi:[1,1]
	v_pk_add_f32 v[204:205], v[204:205], s[2:3] op_sel:[0,1] op_sel_hi:[1,1]
	v_pk_add_f32 v[206:207], v[206:207], s[2:3] op_sel:[0,1] op_sel_hi:[1,1]
	v_rcp_f32_e32 v200, v200
	v_rcp_f32_e32 v201, v201
	v_rcp_f32_e32 v202, v202
	v_rcp_f32_e32 v203, v203
	v_rcp_f32_e32 v204, v204
	v_rcp_f32_e32 v205, v205
	v_rcp_f32_e32 v206, v206
	v_rcp_f32_e32 v207, v207
	v_pk_mul_f32 v[168:169], v[168:169], v[200:201]
	v_pk_mul_f32 v[182:183], v[182:183], v[202:203]
	v_pk_mul_f32 v[184:185], v[184:185], v[204:205]
	v_pk_mul_f32 v[186:187], v[186:187], v[206:207]
	v_pk_mul_f32 v[168:169], v[94:95], v[168:169]
	v_pk_mul_f32 v[182:183], v[96:97], v[182:183]
	v_pk_mul_f32 v[184:185], v[90:91], v[184:185]
	v_pk_mul_f32 v[186:187], v[92:93], v[186:187]
	v_cvt_pk_bf16_f32 v154, v168, v169
	v_cvt_pk_bf16_f32 v155, v182, v183
	v_cvt_pk_bf16_f32 v156, v184, v185
	v_cvt_pk_bf16_f32 v157, v186, v187
	flat_store_dwordx4 v[158:159], v[154:157]
	v_lshl_add_u64 v[158:159], v[158:159], 0, s[6:7]
	v_mov_b32_dpp v192, v118 row_ror:1 row_mask:0xf bank_mask:0xf
	v_mov_b32_dpp v193, v119 row_ror:1 row_mask:0xf bank_mask:0xf
	v_mov_b32_dpp v194, v120 row_ror:1 row_mask:0xf bank_mask:0xf
	v_mov_b32_dpp v195, v121 row_ror:1 row_mask:0xf bank_mask:0xf
	v_mov_b32_dpp v196, v114 row_ror:1 row_mask:0xf bank_mask:0xf
	v_mov_b32_dpp v197, v115 row_ror:1 row_mask:0xf bank_mask:0xf
	v_mov_b32_dpp v198, v116 row_ror:1 row_mask:0xf bank_mask:0xf
	v_mov_b32_dpp v199, v117 row_ror:1 row_mask:0xf bank_mask:0xf
	v_mov_b32_dpp v200, v118 row_ror:2 row_mask:0xf bank_mask:0xf
	v_mov_b32_dpp v201, v119 row_ror:2 row_mask:0xf bank_mask:0xf
	v_mov_b32_dpp v202, v120 row_ror:2 row_mask:0xf bank_mask:0xf
	v_mov_b32_dpp v203, v121 row_ror:2 row_mask:0xf bank_mask:0xf
	v_mov_b32_dpp v204, v114 row_ror:2 row_mask:0xf bank_mask:0xf
	v_mov_b32_dpp v205, v115 row_ror:2 row_mask:0xf bank_mask:0xf
	v_mov_b32_dpp v206, v116 row_ror:2 row_mask:0xf bank_mask:0xf
	v_mov_b32_dpp v207, v117 row_ror:2 row_mask:0xf bank_mask:0xf
	v_cndmask_b32_e64 v208, v208, v192, s[0:1]
	v_cndmask_b32_e64 v209, v209, v193, s[0:1]
	v_cndmask_b32_e64 v210, v210, v194, s[0:1]
	v_cndmask_b32_e64 v211, v211, v195, s[0:1]
	v_cndmask_b32_e64 v212, v212, v196, s[0:1]
	v_cndmask_b32_e64 v213, v213, v197, s[0:1]
	v_cndmask_b32_e64 v214, v214, v198, s[0:1]
	v_cndmask_b32_e64 v215, v215, v199, s[0:1]
	v_cndmask_b32_e64 v160, v160, v200, s[8:9]
	v_cndmask_b32_e64 v161, v161, v201, s[8:9]
	v_cndmask_b32_e64 v162, v162, v202, s[8:9]
	v_cndmask_b32_e64 v163, v163, v203, s[8:9]
	v_cndmask_b32_e64 v164, v164, v204, s[8:9]
	v_cndmask_b32_e64 v165, v165, v205, s[8:9]
	v_cndmask_b32_e64 v166, v166, v206, s[8:9]
	v_cndmask_b32_e64 v167, v167, v207, s[8:9]
	v_pk_mul_f32 v[208:209], v[146:147], v[208:209]
	v_pk_mul_f32 v[210:211], v[148:149], v[210:211]
	v_pk_mul_f32 v[212:213], v[134:135], v[212:213]
	v_pk_mul_f32 v[214:215], v[136:137], v[214:215]
	v_pk_mul_f32 v[168:169], v[118:119], v[150:151]
	v_pk_mul_f32 v[182:183], v[120:121], v[152:153]
	v_pk_mul_f32 v[184:185], v[114:115], v[138:139]
	v_pk_mul_f32 v[186:187], v[116:117], v[140:141]
	v_pk_fma_f32 v[160:161], v[142:143], v[160:161], v[208:209]
	v_pk_fma_f32 v[162:163], v[144:145], v[162:163], v[210:211]
	v_pk_fma_f32 v[164:165], v[130:131], v[164:165], v[212:213]
	v_pk_fma_f32 v[166:167], v[132:133], v[166:167], v[214:215]
	v_pk_add_f32 v[168:169], v[168:169], v[160:161]
	v_pk_add_f32 v[182:183], v[182:183], v[162:163]
	v_pk_add_f32 v[184:185], v[184:185], v[164:165]
	v_pk_add_f32 v[186:187], v[186:187], v[166:167]
	v_pk_mul_f32 v[160:161], v[168:169], s[2:3] op_sel_hi:[1,0]
	v_pk_mul_f32 v[162:163], v[182:183], s[2:3] op_sel_hi:[1,0]
	v_pk_mul_f32 v[164:165], v[184:185], s[2:3] op_sel_hi:[1,0]
	v_pk_mul_f32 v[166:167], v[186:187], s[2:3] op_sel_hi:[1,0]
	v_exp_f32_e32 v160, v160
	v_exp_f32_e32 v161, v161
	v_exp_f32_e32 v162, v162
	v_exp_f32_e32 v163, v163
	v_exp_f32_e32 v164, v164
	v_exp_f32_e32 v165, v165
	v_exp_f32_e32 v166, v166
	v_exp_f32_e32 v167, v167
	v_pk_add_f32 v[160:161], v[160:161], s[2:3] op_sel:[0,1] op_sel_hi:[1,1]
	v_pk_add_f32 v[162:163], v[162:163], s[2:3] op_sel:[0,1] op_sel_hi:[1,1]
	v_pk_add_f32 v[164:165], v[164:165], s[2:3] op_sel:[0,1] op_sel_hi:[1,1]
	v_pk_add_f32 v[166:167], v[166:167], s[2:3] op_sel:[0,1] op_sel_hi:[1,1]
	v_rcp_f32_e32 v160, v160
	v_rcp_f32_e32 v161, v161
	v_rcp_f32_e32 v162, v162
	v_rcp_f32_e32 v163, v163
	v_rcp_f32_e32 v164, v164
	v_rcp_f32_e32 v165, v165
	v_rcp_f32_e32 v166, v166
	v_rcp_f32_e32 v167, v167
	v_pk_mul_f32 v[168:169], v[168:169], v[160:161]
	v_pk_mul_f32 v[182:183], v[182:183], v[162:163]
	v_pk_mul_f32 v[184:185], v[184:185], v[164:165]
	v_pk_mul_f32 v[186:187], v[186:187], v[166:167]
	v_pk_mul_f32 v[168:169], v[86:87], v[168:169]
	v_pk_mul_f32 v[182:183], v[88:89], v[182:183]
	v_pk_mul_f32 v[184:185], v[82:83], v[184:185]
	v_pk_mul_f32 v[186:187], v[84:85], v[186:187]
	v_cvt_pk_bf16_f32 v154, v168, v169
	v_cvt_pk_bf16_f32 v155, v182, v183
	v_cvt_pk_bf16_f32 v156, v184, v185
	v_cvt_pk_bf16_f32 v157, v186, v187
	flat_store_dwordx4 v[158:159], v[154:157]
	v_lshl_add_u64 v[158:159], v[158:159], 0, s[6:7]
	v_mov_b32_dpp v208, v110 row_ror:1 row_mask:0xf bank_mask:0xf
	v_mov_b32_dpp v209, v111 row_ror:1 row_mask:0xf bank_mask:0xf
	v_mov_b32_dpp v210, v112 row_ror:1 row_mask:0xf bank_mask:0xf
	v_mov_b32_dpp v211, v113 row_ror:1 row_mask:0xf bank_mask:0xf
	v_mov_b32_dpp v212, v106 row_ror:1 row_mask:0xf bank_mask:0xf
	v_mov_b32_dpp v213, v107 row_ror:1 row_mask:0xf bank_mask:0xf
	v_mov_b32_dpp v214, v108 row_ror:1 row_mask:0xf bank_mask:0xf
	v_mov_b32_dpp v215, v109 row_ror:1 row_mask:0xf bank_mask:0xf
	v_mov_b32_dpp v160, v110 row_ror:2 row_mask:0xf bank_mask:0xf
	v_mov_b32_dpp v161, v111 row_ror:2 row_mask:0xf bank_mask:0xf
	v_mov_b32_dpp v162, v112 row_ror:2 row_mask:0xf bank_mask:0xf
	v_mov_b32_dpp v163, v113 row_ror:2 row_mask:0xf bank_mask:0xf
	v_mov_b32_dpp v164, v106 row_ror:2 row_mask:0xf bank_mask:0xf
	v_mov_b32_dpp v165, v107 row_ror:2 row_mask:0xf bank_mask:0xf
	v_mov_b32_dpp v166, v108 row_ror:2 row_mask:0xf bank_mask:0xf
	v_mov_b32_dpp v167, v109 row_ror:2 row_mask:0xf bank_mask:0xf
	v_cndmask_b32_e64 v192, v192, v208, s[0:1]
	v_cndmask_b32_e64 v193, v193, v209, s[0:1]
	v_cndmask_b32_e64 v194, v194, v210, s[0:1]
	v_cndmask_b32_e64 v195, v195, v211, s[0:1]
	v_cndmask_b32_e64 v196, v196, v212, s[0:1]
	v_cndmask_b32_e64 v197, v197, v213, s[0:1]
	v_cndmask_b32_e64 v198, v198, v214, s[0:1]
	v_cndmask_b32_e64 v199, v199, v215, s[0:1]
	v_cndmask_b32_e64 v200, v200, v160, s[8:9]
	v_cndmask_b32_e64 v201, v201, v161, s[8:9]
	v_cndmask_b32_e64 v202, v202, v162, s[8:9]
	v_cndmask_b32_e64 v203, v203, v163, s[8:9]
	v_cndmask_b32_e64 v204, v204, v164, s[8:9]
	v_cndmask_b32_e64 v205, v205, v165, s[8:9]
	v_cndmask_b32_e64 v206, v206, v166, s[8:9]
	v_cndmask_b32_e64 v207, v207, v167, s[8:9]
	v_pk_mul_f32 v[192:193], v[146:147], v[192:193]
	v_pk_mul_f32 v[194:195], v[148:149], v[194:195]
	v_pk_mul_f32 v[196:197], v[134:135], v[196:197]
	v_pk_mul_f32 v[198:199], v[136:137], v[198:199]
	v_pk_mul_f32 v[168:169], v[110:111], v[150:151]
	v_pk_mul_f32 v[182:183], v[112:113], v[152:153]
	v_pk_mul_f32 v[184:185], v[106:107], v[138:139]
	v_pk_mul_f32 v[186:187], v[108:109], v[140:141]
	v_pk_fma_f32 v[200:201], v[142:143], v[200:201], v[192:193]
	v_pk_fma_f32 v[202:203], v[144:145], v[202:203], v[194:195]
	v_pk_fma_f32 v[204:205], v[130:131], v[204:205], v[196:197]
	v_pk_fma_f32 v[206:207], v[132:133], v[206:207], v[198:199]
	v_pk_add_f32 v[168:169], v[168:169], v[200:201]
	v_pk_add_f32 v[182:183], v[182:183], v[202:203]
	v_pk_add_f32 v[184:185], v[184:185], v[204:205]
	v_pk_add_f32 v[186:187], v[186:187], v[206:207]
	v_pk_mul_f32 v[200:201], v[168:169], s[2:3] op_sel_hi:[1,0]
	v_pk_mul_f32 v[202:203], v[182:183], s[2:3] op_sel_hi:[1,0]
	v_pk_mul_f32 v[204:205], v[184:185], s[2:3] op_sel_hi:[1,0]
	v_pk_mul_f32 v[206:207], v[186:187], s[2:3] op_sel_hi:[1,0]
	v_exp_f32_e32 v200, v200
	v_exp_f32_e32 v201, v201
	v_exp_f32_e32 v202, v202
	v_exp_f32_e32 v203, v203
	v_exp_f32_e32 v204, v204
	v_exp_f32_e32 v205, v205
	v_exp_f32_e32 v206, v206
	v_exp_f32_e32 v207, v207
	v_pk_add_f32 v[200:201], v[200:201], s[2:3] op_sel:[0,1] op_sel_hi:[1,1]
	v_pk_add_f32 v[202:203], v[202:203], s[2:3] op_sel:[0,1] op_sel_hi:[1,1]
	v_pk_add_f32 v[204:205], v[204:205], s[2:3] op_sel:[0,1] op_sel_hi:[1,1]
	v_pk_add_f32 v[206:207], v[206:207], s[2:3] op_sel:[0,1] op_sel_hi:[1,1]
	v_rcp_f32_e32 v200, v200
	v_rcp_f32_e32 v201, v201
	v_rcp_f32_e32 v202, v202
	v_rcp_f32_e32 v203, v203
	v_rcp_f32_e32 v204, v204
	v_rcp_f32_e32 v205, v205
	v_rcp_f32_e32 v206, v206
	v_rcp_f32_e32 v207, v207
	v_pk_mul_f32 v[168:169], v[168:169], v[200:201]
	v_pk_mul_f32 v[182:183], v[182:183], v[202:203]
	v_pk_mul_f32 v[184:185], v[184:185], v[204:205]
	v_pk_mul_f32 v[186:187], v[186:187], v[206:207]
	v_pk_mul_f32 v[168:169], v[78:79], v[168:169]
	v_pk_mul_f32 v[182:183], v[80:81], v[182:183]
	v_pk_mul_f32 v[184:185], v[74:75], v[184:185]
	v_pk_mul_f32 v[186:187], v[76:77], v[186:187]
	v_cvt_pk_bf16_f32 v154, v168, v169
	v_cvt_pk_bf16_f32 v155, v182, v183
	v_cvt_pk_bf16_f32 v156, v184, v185
	v_cvt_pk_bf16_f32 v157, v186, v187
	flat_store_dwordx4 v[158:159], v[154:157]
	v_lshl_add_u64 v[158:159], v[158:159], 0, s[6:7]
	v_mov_b32_dpp v192, v102 row_ror:1 row_mask:0xf bank_mask:0xf
	v_mov_b32_dpp v193, v103 row_ror:1 row_mask:0xf bank_mask:0xf
	v_mov_b32_dpp v194, v104 row_ror:1 row_mask:0xf bank_mask:0xf
	v_mov_b32_dpp v195, v105 row_ror:1 row_mask:0xf bank_mask:0xf
	v_mov_b32_dpp v196, v98 row_ror:1 row_mask:0xf bank_mask:0xf
	v_mov_b32_dpp v197, v99 row_ror:1 row_mask:0xf bank_mask:0xf
	v_mov_b32_dpp v198, v100 row_ror:1 row_mask:0xf bank_mask:0xf
	v_mov_b32_dpp v199, v101 row_ror:1 row_mask:0xf bank_mask:0xf
	v_mov_b32_dpp v200, v102 row_ror:2 row_mask:0xf bank_mask:0xf
	v_mov_b32_dpp v201, v103 row_ror:2 row_mask:0xf bank_mask:0xf
	v_mov_b32_dpp v202, v104 row_ror:2 row_mask:0xf bank_mask:0xf
	v_mov_b32_dpp v203, v105 row_ror:2 row_mask:0xf bank_mask:0xf
	v_mov_b32_dpp v204, v98 row_ror:2 row_mask:0xf bank_mask:0xf
	v_mov_b32_dpp v205, v99 row_ror:2 row_mask:0xf bank_mask:0xf
	v_mov_b32_dpp v206, v100 row_ror:2 row_mask:0xf bank_mask:0xf
	v_mov_b32_dpp v207, v101 row_ror:2 row_mask:0xf bank_mask:0xf
	v_cndmask_b32_e64 v208, v208, v192, s[0:1]
	v_cndmask_b32_e64 v209, v209, v193, s[0:1]
	v_cndmask_b32_e64 v210, v210, v194, s[0:1]
	v_cndmask_b32_e64 v211, v211, v195, s[0:1]
	v_cndmask_b32_e64 v212, v212, v196, s[0:1]
	v_cndmask_b32_e64 v213, v213, v197, s[0:1]
	v_cndmask_b32_e64 v214, v214, v198, s[0:1]
	v_cndmask_b32_e64 v215, v215, v199, s[0:1]
	v_cndmask_b32_e64 v160, v160, v200, s[8:9]
	v_cndmask_b32_e64 v161, v161, v201, s[8:9]
	v_cndmask_b32_e64 v162, v162, v202, s[8:9]
	v_cndmask_b32_e64 v163, v163, v203, s[8:9]
	v_cndmask_b32_e64 v164, v164, v204, s[8:9]
	v_cndmask_b32_e64 v165, v165, v205, s[8:9]
	v_cndmask_b32_e64 v166, v166, v206, s[8:9]
	v_cndmask_b32_e64 v167, v167, v207, s[8:9]
	v_pk_mul_f32 v[208:209], v[146:147], v[208:209]
	v_pk_mul_f32 v[210:211], v[148:149], v[210:211]
	v_pk_mul_f32 v[212:213], v[134:135], v[212:213]
	v_pk_mul_f32 v[214:215], v[136:137], v[214:215]
	v_pk_mul_f32 v[168:169], v[102:103], v[150:151]
	v_pk_mul_f32 v[182:183], v[104:105], v[152:153]
	v_pk_mul_f32 v[184:185], v[98:99], v[138:139]
	v_pk_mul_f32 v[186:187], v[100:101], v[140:141]
	v_pk_fma_f32 v[160:161], v[142:143], v[160:161], v[208:209]
	v_pk_fma_f32 v[162:163], v[144:145], v[162:163], v[210:211]
	v_pk_fma_f32 v[164:165], v[130:131], v[164:165], v[212:213]
	v_pk_fma_f32 v[166:167], v[132:133], v[166:167], v[214:215]
	v_pk_add_f32 v[168:169], v[168:169], v[160:161]
	v_pk_add_f32 v[182:183], v[182:183], v[162:163]
	v_pk_add_f32 v[184:185], v[184:185], v[164:165]
	v_pk_add_f32 v[186:187], v[186:187], v[166:167]
	v_pk_mul_f32 v[160:161], v[168:169], s[2:3] op_sel_hi:[1,0]
	v_pk_mul_f32 v[162:163], v[182:183], s[2:3] op_sel_hi:[1,0]
	v_pk_mul_f32 v[164:165], v[184:185], s[2:3] op_sel_hi:[1,0]
	v_pk_mul_f32 v[166:167], v[186:187], s[2:3] op_sel_hi:[1,0]
	v_exp_f32_e32 v160, v160
	v_exp_f32_e32 v161, v161
	v_exp_f32_e32 v162, v162
	v_exp_f32_e32 v163, v163
	v_exp_f32_e32 v164, v164
	v_exp_f32_e32 v165, v165
	v_exp_f32_e32 v166, v166
	v_exp_f32_e32 v167, v167
	v_pk_add_f32 v[160:161], v[160:161], s[2:3] op_sel:[0,1] op_sel_hi:[1,1]
	v_pk_add_f32 v[162:163], v[162:163], s[2:3] op_sel:[0,1] op_sel_hi:[1,1]
	v_pk_add_f32 v[164:165], v[164:165], s[2:3] op_sel:[0,1] op_sel_hi:[1,1]
	v_pk_add_f32 v[166:167], v[166:167], s[2:3] op_sel:[0,1] op_sel_hi:[1,1]
	v_rcp_f32_e32 v160, v160
	v_rcp_f32_e32 v161, v161
	v_rcp_f32_e32 v162, v162
	v_rcp_f32_e32 v163, v163
	v_rcp_f32_e32 v164, v164
	v_rcp_f32_e32 v165, v165
	v_rcp_f32_e32 v166, v166
	v_rcp_f32_e32 v167, v167
	v_pk_mul_f32 v[168:169], v[168:169], v[160:161]
	v_pk_mul_f32 v[182:183], v[182:183], v[162:163]
	v_pk_mul_f32 v[184:185], v[184:185], v[164:165]
	v_pk_mul_f32 v[186:187], v[186:187], v[166:167]
	v_pk_mul_f32 v[168:169], v[70:71], v[168:169]
	v_pk_mul_f32 v[182:183], v[72:73], v[182:183]
	v_pk_mul_f32 v[184:185], v[66:67], v[184:185]
	v_pk_mul_f32 v[186:187], v[68:69], v[186:187]
	v_cvt_pk_bf16_f32 v154, v168, v169
	v_cvt_pk_bf16_f32 v155, v182, v183
	v_cvt_pk_bf16_f32 v156, v184, v185
	v_cvt_pk_bf16_f32 v157, v186, v187
	flat_store_dwordx4 v[158:159], v[154:157]
	v_add_co_u32_e32 v158, vcc, 0x6e000, v158
	s_nop 1
	v_addc_co_u32_e32 v159, vcc, 0, v159, vcc
	s_andn2_b64 vcc, exec, s[46:47]
	s_cbranch_vccnz .Lffn_z1
	ds_read_b128 v[200:203], v228 offset:1024
	ds_read_b128 v[192:195], v228 offset:1536
	ds_read_b128 v[204:207], v228 offset:1040
	ds_read_b128 v[196:199], v228 offset:1552
	s_branch .Lffn_d1

.Lffn_d1:
	s_waitcnt lgkmcnt(0)
	v_cndmask_b32_e64 v200, v192, v200, s[4:5]
	v_cndmask_b32_e64 v201, v193, v201, s[4:5]
	v_cndmask_b32_e64 v202, v194, v202, s[4:5]
	v_cndmask_b32_e64 v203, v195, v203, s[4:5]
	v_cndmask_b32_e64 v204, v196, v204, s[4:5]
	v_cndmask_b32_e64 v205, v197, v205, s[4:5]
	v_cndmask_b32_e64 v206, v198, v206, s[4:5]
	v_cndmask_b32_e64 v207, v199, v207, s[4:5]
	v_mov_b32_dpp v208, v62 row_ror:1 row_mask:0xf bank_mask:0xf
	v_mov_b32_dpp v209, v63 row_ror:1 row_mask:0xf bank_mask:0xf
	v_mov_b32_dpp v210, v64 row_ror:1 row_mask:0xf bank_mask:0xf
	v_mov_b32_dpp v211, v65 row_ror:1 row_mask:0xf bank_mask:0xf
	v_mov_b32_dpp v212, v58 row_ror:1 row_mask:0xf bank_mask:0xf
	v_mov_b32_dpp v213, v59 row_ror:1 row_mask:0xf bank_mask:0xf
	v_mov_b32_dpp v214, v60 row_ror:1 row_mask:0xf bank_mask:0xf
	v_mov_b32_dpp v215, v61 row_ror:1 row_mask:0xf bank_mask:0xf
	v_mov_b32_dpp v160, v62 row_ror:2 row_mask:0xf bank_mask:0xf
	v_mov_b32_dpp v161, v63 row_ror:2 row_mask:0xf bank_mask:0xf
	v_mov_b32_dpp v162, v64 row_ror:2 row_mask:0xf bank_mask:0xf
	v_mov_b32_dpp v163, v65 row_ror:2 row_mask:0xf bank_mask:0xf
	v_mov_b32_dpp v164, v58 row_ror:2 row_mask:0xf bank_mask:0xf
	v_mov_b32_dpp v165, v59 row_ror:2 row_mask:0xf bank_mask:0xf
	v_mov_b32_dpp v166, v60 row_ror:2 row_mask:0xf bank_mask:0xf
	v_mov_b32_dpp v167, v61 row_ror:2 row_mask:0xf bank_mask:0xf
	v_cndmask_b32_e64 v192, v192, v208, s[0:1]
	v_cndmask_b32_e64 v193, v193, v209, s[0:1]
	v_cndmask_b32_e64 v194, v194, v210, s[0:1]
	v_cndmask_b32_e64 v195, v195, v211, s[0:1]
	v_cndmask_b32_e64 v196, v196, v212, s[0:1]
	v_cndmask_b32_e64 v197, v197, v213, s[0:1]
	v_cndmask_b32_e64 v198, v198, v214, s[0:1]
	v_cndmask_b32_e64 v199, v199, v215, s[0:1]
	v_cndmask_b32_e64 v200, v200, v160, s[8:9]
	v_cndmask_b32_e64 v201, v201, v161, s[8:9]
	v_cndmask_b32_e64 v202, v202, v162, s[8:9]
	v_cndmask_b32_e64 v203, v203, v163, s[8:9]
	v_cndmask_b32_e64 v204, v204, v164, s[8:9]
	v_cndmask_b32_e64 v205, v205, v165, s[8:9]
	v_cndmask_b32_e64 v206, v206, v166, s[8:9]
	v_cndmask_b32_e64 v207, v207, v167, s[8:9]
	v_pk_mul_f32 v[192:193], v[146:147], v[192:193]
	v_pk_mul_f32 v[194:195], v[148:149], v[194:195]
	v_pk_mul_f32 v[196:197], v[134:135], v[196:197]
	v_pk_mul_f32 v[198:199], v[136:137], v[198:199]
	v_pk_mul_f32 v[168:169], v[62:63], v[150:151]
	v_pk_mul_f32 v[182:183], v[64:65], v[152:153]
	v_pk_mul_f32 v[184:185], v[58:59], v[138:139]
	v_pk_mul_f32 v[186:187], v[60:61], v[140:141]
	v_pk_fma_f32 v[200:201], v[142:143], v[200:201], v[192:193]
	v_pk_fma_f32 v[202:203], v[144:145], v[202:203], v[194:195]
	v_pk_fma_f32 v[204:205], v[130:131], v[204:205], v[196:197]
	v_pk_fma_f32 v[206:207], v[132:133], v[206:207], v[198:199]
	v_pk_add_f32 v[168:169], v[168:169], v[200:201]
	v_pk_add_f32 v[182:183], v[182:183], v[202:203]
	v_pk_add_f32 v[184:185], v[184:185], v[204:205]
	v_pk_add_f32 v[186:187], v[186:187], v[206:207]
	v_pk_mul_f32 v[200:201], v[168:169], s[2:3] op_sel_hi:[1,0]
	v_pk_mul_f32 v[202:203], v[182:183], s[2:3] op_sel_hi:[1,0]
	v_pk_mul_f32 v[204:205], v[184:185], s[2:3] op_sel_hi:[1,0]
	v_pk_mul_f32 v[206:207], v[186:187], s[2:3] op_sel_hi:[1,0]
	v_exp_f32_e32 v200, v200
	v_exp_f32_e32 v201, v201
	v_exp_f32_e32 v202, v202
	v_exp_f32_e32 v203, v203
	v_exp_f32_e32 v204, v204
	v_exp_f32_e32 v205, v205
	v_exp_f32_e32 v206, v206
	v_exp_f32_e32 v207, v207
	v_pk_add_f32 v[200:201], v[200:201], s[2:3] op_sel:[0,1] op_sel_hi:[1,1]
	v_pk_add_f32 v[202:203], v[202:203], s[2:3] op_sel:[0,1] op_sel_hi:[1,1]
	v_pk_add_f32 v[204:205], v[204:205], s[2:3] op_sel:[0,1] op_sel_hi:[1,1]
	v_pk_add_f32 v[206:207], v[206:207], s[2:3] op_sel:[0,1] op_sel_hi:[1,1]
	v_rcp_f32_e32 v200, v200
	v_rcp_f32_e32 v201, v201
	v_rcp_f32_e32 v202, v202
	v_rcp_f32_e32 v203, v203
	v_rcp_f32_e32 v204, v204
	v_rcp_f32_e32 v205, v205
	v_rcp_f32_e32 v206, v206
	v_rcp_f32_e32 v207, v207
	v_pk_mul_f32 v[168:169], v[168:169], v[200:201]
	v_pk_mul_f32 v[182:183], v[182:183], v[202:203]
	v_pk_mul_f32 v[184:185], v[184:185], v[204:205]
	v_pk_mul_f32 v[186:187], v[186:187], v[206:207]
	v_pk_mul_f32 v[168:169], v[30:31], v[168:169]
	v_pk_mul_f32 v[182:183], v[32:33], v[182:183]
	v_pk_mul_f32 v[184:185], v[26:27], v[184:185]
	v_pk_mul_f32 v[186:187], v[28:29], v[186:187]
	v_cvt_pk_bf16_f32 v154, v168, v169
	v_cvt_pk_bf16_f32 v155, v182, v183
	v_cvt_pk_bf16_f32 v156, v184, v185
	v_cvt_pk_bf16_f32 v157, v186, v187
	flat_store_dwordx4 v[158:159], v[154:157]
	v_lshl_add_u64 v[158:159], v[158:159], 0, s[6:7]
	v_mov_b32_dpp v192, v54 row_ror:1 row_mask:0xf bank_mask:0xf
	v_mov_b32_dpp v193, v55 row_ror:1 row_mask:0xf bank_mask:0xf
	v_mov_b32_dpp v194, v56 row_ror:1 row_mask:0xf bank_mask:0xf
	v_mov_b32_dpp v195, v57 row_ror:1 row_mask:0xf bank_mask:0xf
	v_mov_b32_dpp v196, v50 row_ror:1 row_mask:0xf bank_mask:0xf
	v_mov_b32_dpp v197, v51 row_ror:1 row_mask:0xf bank_mask:0xf
	v_mov_b32_dpp v198, v52 row_ror:1 row_mask:0xf bank_mask:0xf
	v_mov_b32_dpp v199, v53 row_ror:1 row_mask:0xf bank_mask:0xf
	v_mov_b32_dpp v200, v54 row_ror:2 row_mask:0xf bank_mask:0xf
	v_mov_b32_dpp v201, v55 row_ror:2 row_mask:0xf bank_mask:0xf
	v_mov_b32_dpp v202, v56 row_ror:2 row_mask:0xf bank_mask:0xf
	v_mov_b32_dpp v203, v57 row_ror:2 row_mask:0xf bank_mask:0xf
	v_mov_b32_dpp v204, v50 row_ror:2 row_mask:0xf bank_mask:0xf
	v_mov_b32_dpp v205, v51 row_ror:2 row_mask:0xf bank_mask:0xf
	v_mov_b32_dpp v206, v52 row_ror:2 row_mask:0xf bank_mask:0xf
	v_mov_b32_dpp v207, v53 row_ror:2 row_mask:0xf bank_mask:0xf
	v_cndmask_b32_e64 v208, v208, v192, s[0:1]
	v_cndmask_b32_e64 v209, v209, v193, s[0:1]
	v_cndmask_b32_e64 v210, v210, v194, s[0:1]
	v_cndmask_b32_e64 v211, v211, v195, s[0:1]
	v_cndmask_b32_e64 v212, v212, v196, s[0:1]
	v_cndmask_b32_e64 v213, v213, v197, s[0:1]
	v_cndmask_b32_e64 v214, v214, v198, s[0:1]
	v_cndmask_b32_e64 v215, v215, v199, s[0:1]
	v_cndmask_b32_e64 v160, v160, v200, s[8:9]
	v_cndmask_b32_e64 v161, v161, v201, s[8:9]
	v_cndmask_b32_e64 v162, v162, v202, s[8:9]
	v_cndmask_b32_e64 v163, v163, v203, s[8:9]
	v_cndmask_b32_e64 v164, v164, v204, s[8:9]
	v_cndmask_b32_e64 v165, v165, v205, s[8:9]
	v_cndmask_b32_e64 v166, v166, v206, s[8:9]
	v_cndmask_b32_e64 v167, v167, v207, s[8:9]
	v_pk_mul_f32 v[208:209], v[146:147], v[208:209]
	v_pk_mul_f32 v[210:211], v[148:149], v[210:211]
	v_pk_mul_f32 v[212:213], v[134:135], v[212:213]
	v_pk_mul_f32 v[214:215], v[136:137], v[214:215]
	v_pk_mul_f32 v[168:169], v[54:55], v[150:151]
	v_pk_mul_f32 v[182:183], v[56:57], v[152:153]
	v_pk_mul_f32 v[184:185], v[50:51], v[138:139]
	v_pk_mul_f32 v[186:187], v[52:53], v[140:141]
	v_pk_fma_f32 v[160:161], v[142:143], v[160:161], v[208:209]
	v_pk_fma_f32 v[162:163], v[144:145], v[162:163], v[210:211]
	v_pk_fma_f32 v[164:165], v[130:131], v[164:165], v[212:213]
	v_pk_fma_f32 v[166:167], v[132:133], v[166:167], v[214:215]
	v_pk_add_f32 v[168:169], v[168:169], v[160:161]
	v_pk_add_f32 v[182:183], v[182:183], v[162:163]
	v_pk_add_f32 v[184:185], v[184:185], v[164:165]
	v_pk_add_f32 v[186:187], v[186:187], v[166:167]
	v_pk_mul_f32 v[160:161], v[168:169], s[2:3] op_sel_hi:[1,0]
	v_pk_mul_f32 v[162:163], v[182:183], s[2:3] op_sel_hi:[1,0]
	v_pk_mul_f32 v[164:165], v[184:185], s[2:3] op_sel_hi:[1,0]
	v_pk_mul_f32 v[166:167], v[186:187], s[2:3] op_sel_hi:[1,0]
	v_exp_f32_e32 v160, v160
	v_exp_f32_e32 v161, v161
	v_exp_f32_e32 v162, v162
	v_exp_f32_e32 v163, v163
	v_exp_f32_e32 v164, v164
	v_exp_f32_e32 v165, v165
	v_exp_f32_e32 v166, v166
	v_exp_f32_e32 v167, v167
	v_pk_add_f32 v[160:161], v[160:161], s[2:3] op_sel:[0,1] op_sel_hi:[1,1]
	v_pk_add_f32 v[162:163], v[162:163], s[2:3] op_sel:[0,1] op_sel_hi:[1,1]
	v_pk_add_f32 v[164:165], v[164:165], s[2:3] op_sel:[0,1] op_sel_hi:[1,1]
	v_pk_add_f32 v[166:167], v[166:167], s[2:3] op_sel:[0,1] op_sel_hi:[1,1]
	v_rcp_f32_e32 v160, v160
	v_rcp_f32_e32 v161, v161
	v_rcp_f32_e32 v162, v162
	v_rcp_f32_e32 v163, v163
	v_rcp_f32_e32 v164, v164
	v_rcp_f32_e32 v165, v165
	v_rcp_f32_e32 v166, v166
	v_rcp_f32_e32 v167, v167
	v_pk_mul_f32 v[168:169], v[168:169], v[160:161]
	v_pk_mul_f32 v[182:183], v[182:183], v[162:163]
	v_pk_mul_f32 v[184:185], v[184:185], v[164:165]
	v_pk_mul_f32 v[186:187], v[186:187], v[166:167]
	v_pk_mul_f32 v[168:169], v[22:23], v[168:169]
	v_pk_mul_f32 v[182:183], v[24:25], v[182:183]
	v_pk_mul_f32 v[184:185], v[18:19], v[184:185]
	v_pk_mul_f32 v[186:187], v[20:21], v[186:187]
	v_cvt_pk_bf16_f32 v154, v168, v169
	v_cvt_pk_bf16_f32 v155, v182, v183
	v_cvt_pk_bf16_f32 v156, v184, v185
	v_cvt_pk_bf16_f32 v157, v186, v187
	flat_store_dwordx4 v[158:159], v[154:157]
	v_lshl_add_u64 v[158:159], v[158:159], 0, s[6:7]
	v_mov_b32_dpp v208, v46 row_ror:1 row_mask:0xf bank_mask:0xf
	v_mov_b32_dpp v209, v47 row_ror:1 row_mask:0xf bank_mask:0xf
	v_mov_b32_dpp v210, v48 row_ror:1 row_mask:0xf bank_mask:0xf
	v_mov_b32_dpp v211, v49 row_ror:1 row_mask:0xf bank_mask:0xf
	v_mov_b32_dpp v212, v42 row_ror:1 row_mask:0xf bank_mask:0xf
	v_mov_b32_dpp v213, v43 row_ror:1 row_mask:0xf bank_mask:0xf
	v_mov_b32_dpp v214, v44 row_ror:1 row_mask:0xf bank_mask:0xf
	v_mov_b32_dpp v215, v45 row_ror:1 row_mask:0xf bank_mask:0xf
	v_mov_b32_dpp v160, v46 row_ror:2 row_mask:0xf bank_mask:0xf
	v_mov_b32_dpp v161, v47 row_ror:2 row_mask:0xf bank_mask:0xf
	v_mov_b32_dpp v162, v48 row_ror:2 row_mask:0xf bank_mask:0xf
	v_mov_b32_dpp v163, v49 row_ror:2 row_mask:0xf bank_mask:0xf
	v_mov_b32_dpp v164, v42 row_ror:2 row_mask:0xf bank_mask:0xf
	v_mov_b32_dpp v165, v43 row_ror:2 row_mask:0xf bank_mask:0xf
	v_mov_b32_dpp v166, v44 row_ror:2 row_mask:0xf bank_mask:0xf
	v_mov_b32_dpp v167, v45 row_ror:2 row_mask:0xf bank_mask:0xf
	v_cndmask_b32_e64 v192, v192, v208, s[0:1]
	v_cndmask_b32_e64 v193, v193, v209, s[0:1]
	v_cndmask_b32_e64 v194, v194, v210, s[0:1]
	v_cndmask_b32_e64 v195, v195, v211, s[0:1]
	v_cndmask_b32_e64 v196, v196, v212, s[0:1]
	v_cndmask_b32_e64 v197, v197, v213, s[0:1]
	v_cndmask_b32_e64 v198, v198, v214, s[0:1]
	v_cndmask_b32_e64 v199, v199, v215, s[0:1]
	v_cndmask_b32_e64 v200, v200, v160, s[8:9]
	v_cndmask_b32_e64 v201, v201, v161, s[8:9]
	v_cndmask_b32_e64 v202, v202, v162, s[8:9]
	v_cndmask_b32_e64 v203, v203, v163, s[8:9]
	v_cndmask_b32_e64 v204, v204, v164, s[8:9]
	v_cndmask_b32_e64 v205, v205, v165, s[8:9]
	v_cndmask_b32_e64 v206, v206, v166, s[8:9]
	v_cndmask_b32_e64 v207, v207, v167, s[8:9]
	v_pk_mul_f32 v[192:193], v[146:147], v[192:193]
	v_pk_mul_f32 v[194:195], v[148:149], v[194:195]
	v_pk_mul_f32 v[196:197], v[134:135], v[196:197]
	v_pk_mul_f32 v[198:199], v[136:137], v[198:199]
	v_pk_mul_f32 v[168:169], v[46:47], v[150:151]
	v_pk_mul_f32 v[182:183], v[48:49], v[152:153]
	v_pk_mul_f32 v[184:185], v[42:43], v[138:139]
	v_pk_mul_f32 v[186:187], v[44:45], v[140:141]
	v_pk_fma_f32 v[200:201], v[142:143], v[200:201], v[192:193]
	v_pk_fma_f32 v[202:203], v[144:145], v[202:203], v[194:195]
	v_pk_fma_f32 v[204:205], v[130:131], v[204:205], v[196:197]
	v_pk_fma_f32 v[206:207], v[132:133], v[206:207], v[198:199]
	v_pk_add_f32 v[168:169], v[168:169], v[200:201]
	v_pk_add_f32 v[182:183], v[182:183], v[202:203]
	v_pk_add_f32 v[184:185], v[184:185], v[204:205]
	v_pk_add_f32 v[186:187], v[186:187], v[206:207]
	v_pk_mul_f32 v[200:201], v[168:169], s[2:3] op_sel_hi:[1,0]
	v_pk_mul_f32 v[202:203], v[182:183], s[2:3] op_sel_hi:[1,0]
	v_pk_mul_f32 v[204:205], v[184:185], s[2:3] op_sel_hi:[1,0]
	v_pk_mul_f32 v[206:207], v[186:187], s[2:3] op_sel_hi:[1,0]
	v_exp_f32_e32 v200, v200
	v_exp_f32_e32 v201, v201
	v_exp_f32_e32 v202, v202
	v_exp_f32_e32 v203, v203
	v_exp_f32_e32 v204, v204
	v_exp_f32_e32 v205, v205
	v_exp_f32_e32 v206, v206
	v_exp_f32_e32 v207, v207
	v_pk_add_f32 v[200:201], v[200:201], s[2:3] op_sel:[0,1] op_sel_hi:[1,1]
	v_pk_add_f32 v[202:203], v[202:203], s[2:3] op_sel:[0,1] op_sel_hi:[1,1]
	v_pk_add_f32 v[204:205], v[204:205], s[2:3] op_sel:[0,1] op_sel_hi:[1,1]
	v_pk_add_f32 v[206:207], v[206:207], s[2:3] op_sel:[0,1] op_sel_hi:[1,1]
	v_rcp_f32_e32 v200, v200
	v_rcp_f32_e32 v201, v201
	v_rcp_f32_e32 v202, v202
	v_rcp_f32_e32 v203, v203
	v_rcp_f32_e32 v204, v204
	v_rcp_f32_e32 v205, v205
	v_rcp_f32_e32 v206, v206
	v_rcp_f32_e32 v207, v207
	v_pk_mul_f32 v[168:169], v[168:169], v[200:201]
	v_pk_mul_f32 v[182:183], v[182:183], v[202:203]
	v_pk_mul_f32 v[184:185], v[184:185], v[204:205]
	v_pk_mul_f32 v[186:187], v[186:187], v[206:207]
	v_pk_mul_f32 v[168:169], v[14:15], v[168:169]
	v_pk_mul_f32 v[182:183], v[16:17], v[182:183]
	v_pk_mul_f32 v[184:185], v[10:11], v[184:185]
	v_pk_mul_f32 v[186:187], v[12:13], v[186:187]
	v_cvt_pk_bf16_f32 v154, v168, v169
	v_cvt_pk_bf16_f32 v155, v182, v183
	v_cvt_pk_bf16_f32 v156, v184, v185
	v_cvt_pk_bf16_f32 v157, v186, v187
	flat_store_dwordx4 v[158:159], v[154:157]
	v_lshl_add_u64 v[158:159], v[158:159], 0, s[6:7]
	v_mov_b32_dpp v192, v38 row_ror:1 row_mask:0xf bank_mask:0xf
	v_mov_b32_dpp v193, v39 row_ror:1 row_mask:0xf bank_mask:0xf
	v_mov_b32_dpp v194, v40 row_ror:1 row_mask:0xf bank_mask:0xf
	v_mov_b32_dpp v195, v41 row_ror:1 row_mask:0xf bank_mask:0xf
	v_mov_b32_dpp v196, v34 row_ror:1 row_mask:0xf bank_mask:0xf
	v_mov_b32_dpp v197, v35 row_ror:1 row_mask:0xf bank_mask:0xf
	v_mov_b32_dpp v198, v36 row_ror:1 row_mask:0xf bank_mask:0xf
	v_mov_b32_dpp v199, v37 row_ror:1 row_mask:0xf bank_mask:0xf
	v_mov_b32_dpp v200, v38 row_ror:2 row_mask:0xf bank_mask:0xf
	v_mov_b32_dpp v201, v39 row_ror:2 row_mask:0xf bank_mask:0xf
	v_mov_b32_dpp v202, v40 row_ror:2 row_mask:0xf bank_mask:0xf
	v_mov_b32_dpp v203, v41 row_ror:2 row_mask:0xf bank_mask:0xf
	v_mov_b32_dpp v204, v34 row_ror:2 row_mask:0xf bank_mask:0xf
	v_mov_b32_dpp v205, v35 row_ror:2 row_mask:0xf bank_mask:0xf
	v_mov_b32_dpp v206, v36 row_ror:2 row_mask:0xf bank_mask:0xf
	v_mov_b32_dpp v207, v37 row_ror:2 row_mask:0xf bank_mask:0xf
	v_cndmask_b32_e64 v208, v208, v192, s[0:1]
	v_cndmask_b32_e64 v209, v209, v193, s[0:1]
	v_cndmask_b32_e64 v210, v210, v194, s[0:1]
	v_cndmask_b32_e64 v211, v211, v195, s[0:1]
	v_cndmask_b32_e64 v212, v212, v196, s[0:1]
	v_cndmask_b32_e64 v213, v213, v197, s[0:1]
	v_cndmask_b32_e64 v214, v214, v198, s[0:1]
	v_cndmask_b32_e64 v215, v215, v199, s[0:1]
	v_cndmask_b32_e64 v160, v160, v200, s[8:9]
	v_cndmask_b32_e64 v161, v161, v201, s[8:9]
	v_cndmask_b32_e64 v162, v162, v202, s[8:9]
	v_cndmask_b32_e64 v163, v163, v203, s[8:9]
	v_cndmask_b32_e64 v164, v164, v204, s[8:9]
	v_cndmask_b32_e64 v165, v165, v205, s[8:9]
	v_cndmask_b32_e64 v166, v166, v206, s[8:9]
	v_cndmask_b32_e64 v167, v167, v207, s[8:9]
	v_pk_mul_f32 v[208:209], v[146:147], v[208:209]
	v_pk_mul_f32 v[210:211], v[148:149], v[210:211]
	v_pk_mul_f32 v[212:213], v[134:135], v[212:213]
	v_pk_mul_f32 v[214:215], v[136:137], v[214:215]
	v_pk_mul_f32 v[168:169], v[38:39], v[150:151]
	v_pk_mul_f32 v[182:183], v[40:41], v[152:153]
	v_pk_mul_f32 v[184:185], v[34:35], v[138:139]
	v_pk_mul_f32 v[186:187], v[36:37], v[140:141]
	v_pk_fma_f32 v[160:161], v[142:143], v[160:161], v[208:209]
	v_pk_fma_f32 v[162:163], v[144:145], v[162:163], v[210:211]
	v_pk_fma_f32 v[164:165], v[130:131], v[164:165], v[212:213]
	v_pk_fma_f32 v[166:167], v[132:133], v[166:167], v[214:215]
	v_pk_add_f32 v[168:169], v[168:169], v[160:161]
	v_pk_add_f32 v[182:183], v[182:183], v[162:163]
	v_pk_add_f32 v[184:185], v[184:185], v[164:165]
	v_pk_add_f32 v[186:187], v[186:187], v[166:167]
	v_pk_mul_f32 v[160:161], v[168:169], s[2:3] op_sel_hi:[1,0]
	v_pk_mul_f32 v[162:163], v[182:183], s[2:3] op_sel_hi:[1,0]
	v_pk_mul_f32 v[164:165], v[184:185], s[2:3] op_sel_hi:[1,0]
	v_pk_mul_f32 v[166:167], v[186:187], s[2:3] op_sel_hi:[1,0]
	v_exp_f32_e32 v160, v160
	v_exp_f32_e32 v161, v161
	v_exp_f32_e32 v162, v162
	v_exp_f32_e32 v163, v163
	v_exp_f32_e32 v164, v164
	v_exp_f32_e32 v165, v165
	v_exp_f32_e32 v166, v166
	v_exp_f32_e32 v167, v167
	v_pk_add_f32 v[160:161], v[160:161], s[2:3] op_sel:[0,1] op_sel_hi:[1,1]
	v_pk_add_f32 v[162:163], v[162:163], s[2:3] op_sel:[0,1] op_sel_hi:[1,1]
	v_pk_add_f32 v[164:165], v[164:165], s[2:3] op_sel:[0,1] op_sel_hi:[1,1]
	v_pk_add_f32 v[166:167], v[166:167], s[2:3] op_sel:[0,1] op_sel_hi:[1,1]
	v_rcp_f32_e32 v160, v160
	v_rcp_f32_e32 v161, v161
	v_rcp_f32_e32 v162, v162
	v_rcp_f32_e32 v163, v163
	v_rcp_f32_e32 v164, v164
	v_rcp_f32_e32 v165, v165
	v_rcp_f32_e32 v166, v166
	v_rcp_f32_e32 v167, v167
	v_pk_mul_f32 v[168:169], v[168:169], v[160:161]
	v_pk_mul_f32 v[182:183], v[182:183], v[162:163]
	v_pk_mul_f32 v[184:185], v[184:185], v[164:165]
	v_pk_mul_f32 v[186:187], v[186:187], v[166:167]
	v_pk_mul_f32 v[168:169], v[6:7], v[168:169]
	v_pk_mul_f32 v[182:183], v[8:9], v[182:183]
	v_pk_mul_f32 v[184:185], v[2:3], v[184:185]
	v_pk_mul_f32 v[186:187], v[4:5], v[186:187]
	v_cvt_pk_bf16_f32 v154, v168, v169
	v_cvt_pk_bf16_f32 v155, v182, v183
	v_cvt_pk_bf16_f32 v156, v184, v185
	v_cvt_pk_bf16_f32 v157, v186, v187
	flat_store_dwordx4 v[158:159], v[154:157]
	s_add_u32 s2, s71, 0xffffff00
	s_addc_u32 s3, s72, -1
	s_andn2_b64 vcc, exec, s[60:61]
	s_cbranch_vccnz .LBB0_337
	s_andn2_b64 vcc, exec, s[28:29]
	s_cbranch_vccnz .LBB0_313
	s_barrier
	s_branch .LBB0_313

.LBB0_1010:
	s_mov_b64 s[8:9], 0x80
	v_lshl_add_u64 v[2:3], v[2:3], 0, s[8:9]
	s_add_i32 m0, s49, 0x18000
	s_waitcnt vmcnt(2)
	s_barrier
	global_load_lds_dwordx4 v[2:3], off
	v_lshl_add_u64 v[2:3], v[4:5], 0, s[8:9]
	s_add_i32 m0, s49, 0x1a000
	s_add_i32 s56, s49, 0x8000
	global_load_lds_dwordx4 v[2:3], off
	v_lshl_add_u64 v[2:3], v[10:11], 0, s[8:9]
	s_mov_b32 m0, s56
	s_add_i32 s57, s49, 0xa000
	global_load_lds_dwordx4 v[2:3], off
	v_lshl_add_u64 v[2:3], v[12:13], 0, s[8:9]
	s_mov_b32 m0, s57
	v_bfe_u32 v179, v14, 4, 2
	global_load_lds_dwordx4 v[2:3], off
	v_lshl_add_u64 v[2:3], v[6:7], 0, s[8:9]
	s_add_i32 m0, s49, 0x1c000
	v_and_b32_e32 v178, 15, v14
	global_load_lds_dwordx4 v[2:3], off
	v_lshl_add_u64 v[2:3], v[8:9], 0, s[8:9]
	s_add_i32 m0, s49, 0x1e000
	v_lshlrev_b32_e32 v0, 4, v179
	global_load_lds_dwordx4 v[2:3], off
	v_lshlrev_b32_e32 v14, 2, v14
	s_and_b32 s4, s3, 3
	v_lshl_or_b32 v0, v178, 6, v0
	s_lshl_b32 s5, s2, 13
	v_and_b32_e32 v14, 32, v14
	s_lshl_b32 s54, s2, 6
	v_bitop3_b32 v18, v0, s5, v14 bitop3:0xde
	s_lshl_b32 s55, s4, 5
	s_lshl_b32 s5, s4, 12
	s_cmpk_lt_u32 s6, 0x100
	s_cselect_b64 s[18:19], -1, 0
	s_add_u32 s20, s82, 0x4e00000
	v_bitop3_b32 v180, v0, s5, v14 bitop3:0xde
	s_addc_u32 s21, s83, 0
	s_bfe_u32 s5, s6, 0x10006
	s_cmp_eq_u32 s5, 0
	s_cselect_b64 s[22:23], -1, 0
	s_lshl_b32 s2, s2, 2
	s_or_b32 s2, s2, s4
	s_bfe_u32 s58, s3, 0x10001
	s_ashr_i32 s3, s2, 31
	s_lshl_b32 s59, s5, 5
	s_lshl_b32 s60, s75, 14
	s_lshl_b64 s[24:25], s[2:3], 10
	s_add_u32 s26, s82, 0xd800000
	s_mul_i32 s2, s7, 0x2600000
	s_addc_u32 s27, s83, 0
	s_ashr_i32 s3, s2, 31
	s_add_u32 s61, s82, 0x15000000
	s_addc_u32 s62, s83, 0
	s_lshr_b32 s63, s12, 3
	s_add_u32 s2, s82, s2
	s_addc_u32 s3, s83, s3
	s_add_u32 s64, s2, 0x100000
	s_addc_u32 s65, s3, 0
	s_add_u32 s28, s82, 0xf000000
	s_addc_u32 s29, s83, 0
	s_add_u32 s30, s82, 0x7800000
	v_lshlrev_b32_e32 v0, 14, v15
	s_addc_u32 s31, s83, 0
	v_and_b32_e32 v0, 0xffff8000, v0
	s_add_u32 s44, s82, 0x5400000
	v_and_b32_e32 v2, 1, v15
	v_lshl_add_u32 v0, v16, 11, v0
	s_waitcnt vmcnt(6)
	v_readlane_b32 s4, v252, 39
	s_addc_u32 s66, s83, 0
	v_lshl_or_b32 v0, v2, 6, v0
	v_readlane_b32 s5, v252, 40
	s_add_u32 s67, s82, 0x5000000
	v_lshl_add_u32 v144, v17, 1, v0
	v_pk_mov_b32 v[2:3], 0, 0
	s_mov_b32 s40, 0
	s_mov_b32 s13, s5
	s_addc_u32 s68, s83, 0
	v_add_u32_e32 v146, 0x20000, v144
	v_mov_b32_e32 v147, v1
	v_mov_b32_e32 v145, v1
	v_add_u32_e32 v181, 0, v18
	v_pk_mov_b32 v[4:5], 0, 0
	v_pk_mov_b32 v[6:7], 0, 0
	v_pk_mov_b32 v[8:9], 0, 0
	v_pk_mov_b32 v[10:11], 0, 0
	v_pk_mov_b32 v[12:13], 0, 0
	v_pk_mov_b32 v[14:15], 0, 0
	v_pk_mov_b32 v[16:17], 0, 0
	v_pk_mov_b32 v[18:19], 0, 0
	v_pk_mov_b32 v[20:21], 0, 0
	v_pk_mov_b32 v[22:23], 0, 0
	v_pk_mov_b32 v[24:25], 0, 0
	v_pk_mov_b32 v[26:27], 0, 0
	v_pk_mov_b32 v[28:29], 0, 0
	v_pk_mov_b32 v[30:31], 0, 0
	v_pk_mov_b32 v[32:33], 0, 0
	v_pk_mov_b32 v[34:35], 0, 0
	v_pk_mov_b32 v[36:37], 0, 0
	v_pk_mov_b32 v[38:39], 0, 0
	v_pk_mov_b32 v[40:41], 0, 0
	v_pk_mov_b32 v[42:43], 0, 0
	v_pk_mov_b32 v[44:45], 0, 0
	v_pk_mov_b32 v[46:47], 0, 0
	v_pk_mov_b32 v[48:49], 0, 0
	v_pk_mov_b32 v[50:51], 0, 0
	v_pk_mov_b32 v[52:53], 0, 0
	v_pk_mov_b32 v[54:55], 0, 0
	v_pk_mov_b32 v[56:57], 0, 0
	v_pk_mov_b32 v[58:59], 0, 0
	v_pk_mov_b32 v[60:61], 0, 0
	v_pk_mov_b32 v[62:63], 0, 0
	v_pk_mov_b32 v[64:65], 0, 0
	v_pk_mov_b32 v[66:67], 0, 0
	v_pk_mov_b32 v[68:69], 0, 0
	v_pk_mov_b32 v[70:71], 0, 0
	v_pk_mov_b32 v[72:73], 0, 0
	v_pk_mov_b32 v[74:75], 0, 0
	v_pk_mov_b32 v[76:77], 0, 0
	v_pk_mov_b32 v[78:79], 0, 0
	v_pk_mov_b32 v[80:81], 0, 0
	v_pk_mov_b32 v[82:83], 0, 0
	v_pk_mov_b32 v[84:85], 0, 0
	v_pk_mov_b32 v[86:87], 0, 0
	v_pk_mov_b32 v[88:89], 0, 0
	v_pk_mov_b32 v[90:91], 0, 0
	v_pk_mov_b32 v[92:93], 0, 0
	v_pk_mov_b32 v[94:95], 0, 0
	v_pk_mov_b32 v[96:97], 0, 0
	v_pk_mov_b32 v[98:99], 0, 0
	v_pk_mov_b32 v[100:101], 0, 0
	v_pk_mov_b32 v[102:103], 0, 0
	v_pk_mov_b32 v[104:105], 0, 0
	v_pk_mov_b32 v[106:107], 0, 0
	v_pk_mov_b32 v[108:109], 0, 0
	v_pk_mov_b32 v[110:111], 0, 0
	v_pk_mov_b32 v[112:113], 0, 0
	v_pk_mov_b32 v[114:115], 0, 0
	v_pk_mov_b32 v[116:117], 0, 0
	v_pk_mov_b32 v[118:119], 0, 0
	v_pk_mov_b32 v[120:121], 0, 0
	v_pk_mov_b32 v[122:123], 0, 0
	v_pk_mov_b32 v[124:125], 0, 0
	v_pk_mov_b32 v[126:127], 0, 0
	v_pk_mov_b32 v[128:129], 0, 0
	s_mov_b64 s[38:39], s[0:1]
	s_barrier
	s_branch .LBB0_1012
.LBB0_1011:
	v_pk_mov_b32 v[2:3], 0, 0
	v_pk_mov_b32 v[4:5], 0, 0
	v_pk_mov_b32 v[6:7], 0, 0
	v_pk_mov_b32 v[8:9], 0, 0
	v_pk_mov_b32 v[10:11], 0, 0
	v_pk_mov_b32 v[12:13], 0, 0
	v_pk_mov_b32 v[14:15], 0, 0
	v_pk_mov_b32 v[16:17], 0, 0
	v_pk_mov_b32 v[18:19], 0, 0
	v_pk_mov_b32 v[20:21], 0, 0
	v_pk_mov_b32 v[22:23], 0, 0
	v_pk_mov_b32 v[24:25], 0, 0
	v_pk_mov_b32 v[26:27], 0, 0
	v_pk_mov_b32 v[28:29], 0, 0
	v_pk_mov_b32 v[30:31], 0, 0
	v_pk_mov_b32 v[32:33], 0, 0
	v_pk_mov_b32 v[34:35], 0, 0
	v_pk_mov_b32 v[36:37], 0, 0
	v_pk_mov_b32 v[38:39], 0, 0
	v_pk_mov_b32 v[40:41], 0, 0
	v_pk_mov_b32 v[42:43], 0, 0
	v_pk_mov_b32 v[44:45], 0, 0
	v_pk_mov_b32 v[46:47], 0, 0
	v_pk_mov_b32 v[48:49], 0, 0
	v_pk_mov_b32 v[50:51], 0, 0
	v_pk_mov_b32 v[52:53], 0, 0
	v_pk_mov_b32 v[54:55], 0, 0
	v_pk_mov_b32 v[56:57], 0, 0
	v_pk_mov_b32 v[58:59], 0, 0
	v_pk_mov_b32 v[60:61], 0, 0
	v_pk_mov_b32 v[62:63], 0, 0
	v_pk_mov_b32 v[64:65], 0, 0
	v_pk_mov_b32 v[66:67], 0, 0
	v_pk_mov_b32 v[68:69], 0, 0
	v_pk_mov_b32 v[70:71], 0, 0
	v_pk_mov_b32 v[72:73], 0, 0
	v_pk_mov_b32 v[74:75], 0, 0
	v_pk_mov_b32 v[76:77], 0, 0
	v_pk_mov_b32 v[78:79], 0, 0
	v_pk_mov_b32 v[80:81], 0, 0
	v_pk_mov_b32 v[82:83], 0, 0
	v_pk_mov_b32 v[84:85], 0, 0
	v_pk_mov_b32 v[86:87], 0, 0
	v_pk_mov_b32 v[88:89], 0, 0
	v_pk_mov_b32 v[90:91], 0, 0
	v_pk_mov_b32 v[92:93], 0, 0
	v_pk_mov_b32 v[94:95], 0, 0
	v_pk_mov_b32 v[96:97], 0, 0
	v_pk_mov_b32 v[98:99], 0, 0
	v_pk_mov_b32 v[100:101], 0, 0
	v_pk_mov_b32 v[102:103], 0, 0
	v_pk_mov_b32 v[104:105], 0, 0
	v_pk_mov_b32 v[106:107], 0, 0
	v_pk_mov_b32 v[108:109], 0, 0
	v_pk_mov_b32 v[110:111], 0, 0
	v_pk_mov_b32 v[112:113], 0, 0
	v_pk_mov_b32 v[114:115], 0, 0
	v_pk_mov_b32 v[116:117], 0, 0
	v_pk_mov_b32 v[118:119], 0, 0
	v_pk_mov_b32 v[120:121], 0, 0
	v_pk_mov_b32 v[122:123], 0, 0
	v_pk_mov_b32 v[124:125], 0, 0
	v_pk_mov_b32 v[126:127], 0, 0
	v_pk_mov_b32 v[128:129], 0, 0
	s_mov_b32 s50, s73
	s_mov_b64 s[14:15], s[46:47]
	s_mov_b32 s40, s72
	s_andn2_b64 vcc, exec, s[8:9]
	s_mov_b64 s[0:1], s[38:39]
	s_cbranch_vccz .LBB0_1126

.LBB0_1113:
	s_andn2_b64 vcc, exec, s[0:1]
	s_cbranch_vccnz .LBB0_1118
	s_cmp_gt_i32 s2, 1
	s_mov_b64 s[0:1], -1
	s_cbranch_scc0 .LBB0_1116
	v_lshlrev_b32_e32 v0, 3, v183
	v_lshl_add_u32 v130, v182, 7, v0
	s_mul_i32 s0, s70, 12
	s_add_i32 s0, s0, s69
	s_ashr_i32 s1, s0, 31
	s_lshl_b64 s[0:1], s[0:1], 17
	s_add_u32 s0, s34, s0
	s_addc_u32 s1, s35, s1
	s_add_u32 s0, s0, s24
	s_addc_u32 s1, s1, s25
	v_ashrrev_i32_e32 v131, 31, v130
	v_lshl_add_u64 v[130:131], v[130:131], 1, s[0:1]
	s_mov_b32 s0, 0xbfb8aa3b
	s_mov_b32 s1, 1.0
	s_mov_b32 s6, 0x2000
	s_mov_b32 s7, 0
	v_pk_mul_f32 v[148:149], v[126:127], s[0:1] op_sel_hi:[1,0]
	v_pk_mul_f32 v[150:151], v[128:129], s[0:1] op_sel_hi:[1,0]
	v_pk_mul_f32 v[152:153], v[122:123], s[0:1] op_sel_hi:[1,0]
	v_pk_mul_f32 v[154:155], v[124:125], s[0:1] op_sel_hi:[1,0]
	v_exp_f32_e32 v148, v148
	v_exp_f32_e32 v149, v149
	v_exp_f32_e32 v150, v150
	v_exp_f32_e32 v151, v151
	v_exp_f32_e32 v152, v152
	v_exp_f32_e32 v153, v153
	v_exp_f32_e32 v154, v154
	v_exp_f32_e32 v155, v155
	v_pk_add_f32 v[148:149], v[148:149], s[0:1] op_sel:[0,1] op_sel_hi:[1,1]
	v_pk_add_f32 v[150:151], v[150:151], s[0:1] op_sel:[0,1] op_sel_hi:[1,1]
	v_pk_add_f32 v[152:153], v[152:153], s[0:1] op_sel:[0,1] op_sel_hi:[1,1]
	v_pk_add_f32 v[154:155], v[154:155], s[0:1] op_sel:[0,1] op_sel_hi:[1,1]
	v_rcp_f32_e32 v148, v148
	v_rcp_f32_e32 v149, v149
	v_rcp_f32_e32 v150, v150
	v_rcp_f32_e32 v151, v151
	v_rcp_f32_e32 v152, v152
	v_rcp_f32_e32 v153, v153
	v_rcp_f32_e32 v154, v154
	v_rcp_f32_e32 v155, v155
	v_max_f32_e32 v148, 0x1e3ce508, v148
	v_max_f32_e32 v149, 0x1e3ce508, v149
	v_max_f32_e32 v150, 0x1e3ce508, v150
	v_max_f32_e32 v151, 0x1e3ce508, v151
	v_max_f32_e32 v152, 0x1e3ce508, v152
	v_max_f32_e32 v153, 0x1e3ce508, v153
	v_max_f32_e32 v154, 0x1e3ce508, v154
	v_max_f32_e32 v155, 0x1e3ce508, v155
	v_cvt_pk_bf16_f32 v132, v148, v149
	v_cvt_pk_bf16_f32 v133, v150, v151
	v_cvt_pk_bf16_f32 v134, v152, v153
	v_cvt_pk_bf16_f32 v135, v154, v155
	flat_store_dwordx4 v[130:131], v[132:135]
	v_lshl_add_u64 v[130:131], v[130:131], 0, s[6:7]
	v_pk_mul_f32 v[148:149], v[94:95], s[0:1] op_sel_hi:[1,0]
	v_pk_mul_f32 v[150:151], v[96:97], s[0:1] op_sel_hi:[1,0]
	v_pk_mul_f32 v[152:153], v[90:91], s[0:1] op_sel_hi:[1,0]
	v_pk_mul_f32 v[154:155], v[92:93], s[0:1] op_sel_hi:[1,0]
	v_exp_f32_e32 v148, v148
	v_exp_f32_e32 v149, v149
	v_exp_f32_e32 v150, v150
	v_exp_f32_e32 v151, v151
	v_exp_f32_e32 v152, v152
	v_exp_f32_e32 v153, v153
	v_exp_f32_e32 v154, v154
	v_exp_f32_e32 v155, v155
	v_pk_add_f32 v[148:149], v[148:149], s[0:1] op_sel:[0,1] op_sel_hi:[1,1]
	v_pk_add_f32 v[150:151], v[150:151], s[0:1] op_sel:[0,1] op_sel_hi:[1,1]
	v_pk_add_f32 v[152:153], v[152:153], s[0:1] op_sel:[0,1] op_sel_hi:[1,1]
	v_pk_add_f32 v[154:155], v[154:155], s[0:1] op_sel:[0,1] op_sel_hi:[1,1]
	v_rcp_f32_e32 v148, v148
	v_rcp_f32_e32 v149, v149
	v_rcp_f32_e32 v150, v150
	v_rcp_f32_e32 v151, v151
	v_rcp_f32_e32 v152, v152
	v_rcp_f32_e32 v153, v153
	v_rcp_f32_e32 v154, v154
	v_rcp_f32_e32 v155, v155
	v_max_f32_e32 v148, 0x1e3ce508, v148
	v_max_f32_e32 v149, 0x1e3ce508, v149
	v_max_f32_e32 v150, 0x1e3ce508, v150
	v_max_f32_e32 v151, 0x1e3ce508, v151
	v_max_f32_e32 v152, 0x1e3ce508, v152
	v_max_f32_e32 v153, 0x1e3ce508, v153
	v_max_f32_e32 v154, 0x1e3ce508, v154
	v_max_f32_e32 v155, 0x1e3ce508, v155
	v_cvt_pk_bf16_f32 v132, v148, v149
	v_cvt_pk_bf16_f32 v133, v150, v151
	v_cvt_pk_bf16_f32 v134, v152, v153
	v_cvt_pk_bf16_f32 v135, v154, v155
	flat_store_dwordx4 v[130:131], v[132:135]
	v_lshl_add_u64 v[130:131], v[130:131], 0, s[6:7]
	v_pk_mul_f32 v[148:149], v[118:119], s[0:1] op_sel_hi:[1,0]
	v_pk_mul_f32 v[150:151], v[120:121], s[0:1] op_sel_hi:[1,0]
	v_pk_mul_f32 v[152:153], v[114:115], s[0:1] op_sel_hi:[1,0]
	v_pk_mul_f32 v[154:155], v[116:117], s[0:1] op_sel_hi:[1,0]
	v_exp_f32_e32 v148, v148
	v_exp_f32_e32 v149, v149
	v_exp_f32_e32 v150, v150
	v_exp_f32_e32 v151, v151
	v_exp_f32_e32 v152, v152
	v_exp_f32_e32 v153, v153
	v_exp_f32_e32 v154, v154
	v_exp_f32_e32 v155, v155
	v_pk_add_f32 v[148:149], v[148:149], s[0:1] op_sel:[0,1] op_sel_hi:[1,1]
	v_pk_add_f32 v[150:151], v[150:151], s[0:1] op_sel:[0,1] op_sel_hi:[1,1]
	v_pk_add_f32 v[152:153], v[152:153], s[0:1] op_sel:[0,1] op_sel_hi:[1,1]
	v_pk_add_f32 v[154:155], v[154:155], s[0:1] op_sel:[0,1] op_sel_hi:[1,1]
	v_rcp_f32_e32 v148, v148
	v_rcp_f32_e32 v149, v149
	v_rcp_f32_e32 v150, v150
	v_rcp_f32_e32 v151, v151
	v_rcp_f32_e32 v152, v152
	v_rcp_f32_e32 v153, v153
	v_rcp_f32_e32 v154, v154
	v_rcp_f32_e32 v155, v155
	v_max_f32_e32 v148, 0x1e3ce508, v148
	v_max_f32_e32 v149, 0x1e3ce508, v149
	v_max_f32_e32 v150, 0x1e3ce508, v150
	v_max_f32_e32 v151, 0x1e3ce508, v151
	v_max_f32_e32 v152, 0x1e3ce508, v152
	v_max_f32_e32 v153, 0x1e3ce508, v153
	v_max_f32_e32 v154, 0x1e3ce508, v154
	v_max_f32_e32 v155, 0x1e3ce508, v155
	v_cvt_pk_bf16_f32 v132, v148, v149
	v_cvt_pk_bf16_f32 v133, v150, v151
	v_cvt_pk_bf16_f32 v134, v152, v153
	v_cvt_pk_bf16_f32 v135, v154, v155
	flat_store_dwordx4 v[130:131], v[132:135]
	v_lshl_add_u64 v[130:131], v[130:131], 0, s[6:7]
	v_pk_mul_f32 v[148:149], v[86:87], s[0:1] op_sel_hi:[1,0]
	v_pk_mul_f32 v[150:151], v[88:89], s[0:1] op_sel_hi:[1,0]
	v_pk_mul_f32 v[152:153], v[82:83], s[0:1] op_sel_hi:[1,0]
	v_pk_mul_f32 v[154:155], v[84:85], s[0:1] op_sel_hi:[1,0]
	v_exp_f32_e32 v148, v148
	v_exp_f32_e32 v149, v149
	v_exp_f32_e32 v150, v150
	v_exp_f32_e32 v151, v151
	v_exp_f32_e32 v152, v152
	v_exp_f32_e32 v153, v153
	v_exp_f32_e32 v154, v154
	v_exp_f32_e32 v155, v155
	v_pk_add_f32 v[148:149], v[148:149], s[0:1] op_sel:[0,1] op_sel_hi:[1,1]
	v_pk_add_f32 v[150:151], v[150:151], s[0:1] op_sel:[0,1] op_sel_hi:[1,1]
	v_pk_add_f32 v[152:153], v[152:153], s[0:1] op_sel:[0,1] op_sel_hi:[1,1]
	v_pk_add_f32 v[154:155], v[154:155], s[0:1] op_sel:[0,1] op_sel_hi:[1,1]
	v_rcp_f32_e32 v148, v148
	v_rcp_f32_e32 v149, v149
	v_rcp_f32_e32 v150, v150
	v_rcp_f32_e32 v151, v151
	v_rcp_f32_e32 v152, v152
	v_rcp_f32_e32 v153, v153
	v_rcp_f32_e32 v154, v154
	v_rcp_f32_e32 v155, v155
	v_max_f32_e32 v148, 0x1e3ce508, v148
	v_max_f32_e32 v149, 0x1e3ce508, v149
	v_max_f32_e32 v150, 0x1e3ce508, v150
	v_max_f32_e32 v151, 0x1e3ce508, v151
	v_max_f32_e32 v152, 0x1e3ce508, v152
	v_max_f32_e32 v153, 0x1e3ce508, v153
	v_max_f32_e32 v154, 0x1e3ce508, v154
	v_max_f32_e32 v155, 0x1e3ce508, v155
	v_cvt_pk_bf16_f32 v132, v148, v149
	v_cvt_pk_bf16_f32 v133, v150, v151
	v_cvt_pk_bf16_f32 v134, v152, v153
	v_cvt_pk_bf16_f32 v135, v154, v155
	flat_store_dwordx4 v[130:131], v[132:135]
	v_lshl_add_u64 v[130:131], v[130:131], 0, s[6:7]
	v_pk_mul_f32 v[148:149], v[110:111], s[0:1] op_sel_hi:[1,0]
	v_pk_mul_f32 v[150:151], v[112:113], s[0:1] op_sel_hi:[1,0]
	v_pk_mul_f32 v[152:153], v[106:107], s[0:1] op_sel_hi:[1,0]
	v_pk_mul_f32 v[154:155], v[108:109], s[0:1] op_sel_hi:[1,0]
	v_exp_f32_e32 v148, v148
	v_exp_f32_e32 v149, v149
	v_exp_f32_e32 v150, v150
	v_exp_f32_e32 v151, v151
	v_exp_f32_e32 v152, v152
	v_exp_f32_e32 v153, v153
	v_exp_f32_e32 v154, v154
	v_exp_f32_e32 v155, v155
	v_pk_add_f32 v[148:149], v[148:149], s[0:1] op_sel:[0,1] op_sel_hi:[1,1]
	v_pk_add_f32 v[150:151], v[150:151], s[0:1] op_sel:[0,1] op_sel_hi:[1,1]
	v_pk_add_f32 v[152:153], v[152:153], s[0:1] op_sel:[0,1] op_sel_hi:[1,1]
	v_pk_add_f32 v[154:155], v[154:155], s[0:1] op_sel:[0,1] op_sel_hi:[1,1]
	v_rcp_f32_e32 v148, v148
	v_rcp_f32_e32 v149, v149
	v_rcp_f32_e32 v150, v150
	v_rcp_f32_e32 v151, v151
	v_rcp_f32_e32 v152, v152
	v_rcp_f32_e32 v153, v153
	v_rcp_f32_e32 v154, v154
	v_rcp_f32_e32 v155, v155
	v_max_f32_e32 v148, 0x1e3ce508, v148
	v_max_f32_e32 v149, 0x1e3ce508, v149
	v_max_f32_e32 v150, 0x1e3ce508, v150
	v_max_f32_e32 v151, 0x1e3ce508, v151
	v_max_f32_e32 v152, 0x1e3ce508, v152
	v_max_f32_e32 v153, 0x1e3ce508, v153
	v_max_f32_e32 v154, 0x1e3ce508, v154
	v_max_f32_e32 v155, 0x1e3ce508, v155
	v_cvt_pk_bf16_f32 v132, v148, v149
	v_cvt_pk_bf16_f32 v133, v150, v151
	v_cvt_pk_bf16_f32 v134, v152, v153
	v_cvt_pk_bf16_f32 v135, v154, v155
	flat_store_dwordx4 v[130:131], v[132:135]
	v_lshl_add_u64 v[130:131], v[130:131], 0, s[6:7]
	v_pk_mul_f32 v[148:149], v[78:79], s[0:1] op_sel_hi:[1,0]
	v_pk_mul_f32 v[150:151], v[80:81], s[0:1] op_sel_hi:[1,0]
	v_pk_mul_f32 v[152:153], v[74:75], s[0:1] op_sel_hi:[1,0]
	v_pk_mul_f32 v[154:155], v[76:77], s[0:1] op_sel_hi:[1,0]
	v_exp_f32_e32 v148, v148
	v_exp_f32_e32 v149, v149
	v_exp_f32_e32 v150, v150
	v_exp_f32_e32 v151, v151
	v_exp_f32_e32 v152, v152
	v_exp_f32_e32 v153, v153
	v_exp_f32_e32 v154, v154
	v_exp_f32_e32 v155, v155
	v_pk_add_f32 v[148:149], v[148:149], s[0:1] op_sel:[0,1] op_sel_hi:[1,1]
	v_pk_add_f32 v[150:151], v[150:151], s[0:1] op_sel:[0,1] op_sel_hi:[1,1]
	v_pk_add_f32 v[152:153], v[152:153], s[0:1] op_sel:[0,1] op_sel_hi:[1,1]
	v_pk_add_f32 v[154:155], v[154:155], s[0:1] op_sel:[0,1] op_sel_hi:[1,1]
	v_rcp_f32_e32 v148, v148
	v_rcp_f32_e32 v149, v149
	v_rcp_f32_e32 v150, v150
	v_rcp_f32_e32 v151, v151
	v_rcp_f32_e32 v152, v152
	v_rcp_f32_e32 v153, v153
	v_rcp_f32_e32 v154, v154
	v_rcp_f32_e32 v155, v155
	v_max_f32_e32 v148, 0x1e3ce508, v148
	v_max_f32_e32 v149, 0x1e3ce508, v149
	v_max_f32_e32 v150, 0x1e3ce508, v150
	v_max_f32_e32 v151, 0x1e3ce508, v151
	v_max_f32_e32 v152, 0x1e3ce508, v152
	v_max_f32_e32 v153, 0x1e3ce508, v153
	v_max_f32_e32 v154, 0x1e3ce508, v154
	v_max_f32_e32 v155, 0x1e3ce508, v155
	v_cvt_pk_bf16_f32 v132, v148, v149
	v_cvt_pk_bf16_f32 v133, v150, v151
	v_cvt_pk_bf16_f32 v134, v152, v153
	v_cvt_pk_bf16_f32 v135, v154, v155
	flat_store_dwordx4 v[130:131], v[132:135]
	v_lshl_add_u64 v[130:131], v[130:131], 0, s[6:7]
	v_pk_mul_f32 v[148:149], v[102:103], s[0:1] op_sel_hi:[1,0]
	v_pk_mul_f32 v[150:151], v[104:105], s[0:1] op_sel_hi:[1,0]
	v_pk_mul_f32 v[152:153], v[98:99], s[0:1] op_sel_hi:[1,0]
	v_pk_mul_f32 v[154:155], v[100:101], s[0:1] op_sel_hi:[1,0]
	v_exp_f32_e32 v148, v148
	v_exp_f32_e32 v149, v149
	v_exp_f32_e32 v150, v150
	v_exp_f32_e32 v151, v151
	v_exp_f32_e32 v152, v152
	v_exp_f32_e32 v153, v153
	v_exp_f32_e32 v154, v154
	v_exp_f32_e32 v155, v155
	v_pk_add_f32 v[148:149], v[148:149], s[0:1] op_sel:[0,1] op_sel_hi:[1,1]
	v_pk_add_f32 v[150:151], v[150:151], s[0:1] op_sel:[0,1] op_sel_hi:[1,1]
	v_pk_add_f32 v[152:153], v[152:153], s[0:1] op_sel:[0,1] op_sel_hi:[1,1]
	v_pk_add_f32 v[154:155], v[154:155], s[0:1] op_sel:[0,1] op_sel_hi:[1,1]
	v_rcp_f32_e32 v148, v148
	v_rcp_f32_e32 v149, v149
	v_rcp_f32_e32 v150, v150
	v_rcp_f32_e32 v151, v151
	v_rcp_f32_e32 v152, v152
	v_rcp_f32_e32 v153, v153
	v_rcp_f32_e32 v154, v154
	v_rcp_f32_e32 v155, v155
	v_max_f32_e32 v148, 0x1e3ce508, v148
	v_max_f32_e32 v149, 0x1e3ce508, v149
	v_max_f32_e32 v150, 0x1e3ce508, v150
	v_max_f32_e32 v151, 0x1e3ce508, v151
	v_max_f32_e32 v152, 0x1e3ce508, v152
	v_max_f32_e32 v153, 0x1e3ce508, v153
	v_max_f32_e32 v154, 0x1e3ce508, v154
	v_max_f32_e32 v155, 0x1e3ce508, v155
	v_cvt_pk_bf16_f32 v132, v148, v149
	v_cvt_pk_bf16_f32 v133, v150, v151
	v_cvt_pk_bf16_f32 v134, v152, v153
	v_cvt_pk_bf16_f32 v135, v154, v155
	flat_store_dwordx4 v[130:131], v[132:135]
	v_lshl_add_u64 v[130:131], v[130:131], 0, s[6:7]
	v_pk_mul_f32 v[148:149], v[70:71], s[0:1] op_sel_hi:[1,0]
	v_pk_mul_f32 v[150:151], v[72:73], s[0:1] op_sel_hi:[1,0]
	v_pk_mul_f32 v[152:153], v[66:67], s[0:1] op_sel_hi:[1,0]
	v_pk_mul_f32 v[154:155], v[68:69], s[0:1] op_sel_hi:[1,0]
	v_exp_f32_e32 v148, v148
	v_exp_f32_e32 v149, v149
	v_exp_f32_e32 v150, v150
	v_exp_f32_e32 v151, v151
	v_exp_f32_e32 v152, v152
	v_exp_f32_e32 v153, v153
	v_exp_f32_e32 v154, v154
	v_exp_f32_e32 v155, v155
	v_pk_add_f32 v[148:149], v[148:149], s[0:1] op_sel:[0,1] op_sel_hi:[1,1]
	v_pk_add_f32 v[150:151], v[150:151], s[0:1] op_sel:[0,1] op_sel_hi:[1,1]
	v_pk_add_f32 v[152:153], v[152:153], s[0:1] op_sel:[0,1] op_sel_hi:[1,1]
	v_pk_add_f32 v[154:155], v[154:155], s[0:1] op_sel:[0,1] op_sel_hi:[1,1]
	v_rcp_f32_e32 v148, v148
	v_rcp_f32_e32 v149, v149
	v_rcp_f32_e32 v150, v150
	v_rcp_f32_e32 v151, v151
	v_rcp_f32_e32 v152, v152
	v_rcp_f32_e32 v153, v153
	v_rcp_f32_e32 v154, v154
	v_rcp_f32_e32 v155, v155
	v_max_f32_e32 v148, 0x1e3ce508, v148
	v_max_f32_e32 v149, 0x1e3ce508, v149
	v_max_f32_e32 v150, 0x1e3ce508, v150
	v_max_f32_e32 v151, 0x1e3ce508, v151
	v_max_f32_e32 v152, 0x1e3ce508, v152
	v_max_f32_e32 v153, 0x1e3ce508, v153
	v_max_f32_e32 v154, 0x1e3ce508, v154
	v_max_f32_e32 v155, 0x1e3ce508, v155
	v_cvt_pk_bf16_f32 v132, v148, v149
	v_cvt_pk_bf16_f32 v133, v150, v151
	v_cvt_pk_bf16_f32 v134, v152, v153
	v_cvt_pk_bf16_f32 v135, v154, v155
	flat_store_dwordx4 v[130:131], v[132:135]
	v_lshl_add_u64 v[130:131], v[130:131], 0, s[6:7]
	v_pk_mul_f32 v[148:149], v[62:63], s[0:1] op_sel_hi:[1,0]
	v_pk_mul_f32 v[150:151], v[64:65], s[0:1] op_sel_hi:[1,0]
	v_pk_mul_f32 v[152:153], v[58:59], s[0:1] op_sel_hi:[1,0]
	v_pk_mul_f32 v[154:155], v[60:61], s[0:1] op_sel_hi:[1,0]
	v_exp_f32_e32 v148, v148
	v_exp_f32_e32 v149, v149
	v_exp_f32_e32 v150, v150
	v_exp_f32_e32 v151, v151
	v_exp_f32_e32 v152, v152
	v_exp_f32_e32 v153, v153
	v_exp_f32_e32 v154, v154
	v_exp_f32_e32 v155, v155
	v_pk_add_f32 v[148:149], v[148:149], s[0:1] op_sel:[0,1] op_sel_hi:[1,1]
	v_pk_add_f32 v[150:151], v[150:151], s[0:1] op_sel:[0,1] op_sel_hi:[1,1]
	v_pk_add_f32 v[152:153], v[152:153], s[0:1] op_sel:[0,1] op_sel_hi:[1,1]
	v_pk_add_f32 v[154:155], v[154:155], s[0:1] op_sel:[0,1] op_sel_hi:[1,1]
	v_rcp_f32_e32 v148, v148
	v_rcp_f32_e32 v149, v149
	v_rcp_f32_e32 v150, v150
	v_rcp_f32_e32 v151, v151
	v_rcp_f32_e32 v152, v152
	v_rcp_f32_e32 v153, v153
	v_rcp_f32_e32 v154, v154
	v_rcp_f32_e32 v155, v155
	v_max_f32_e32 v148, 0x1e3ce508, v148
	v_max_f32_e32 v149, 0x1e3ce508, v149
	v_max_f32_e32 v150, 0x1e3ce508, v150
	v_max_f32_e32 v151, 0x1e3ce508, v151
	v_max_f32_e32 v152, 0x1e3ce508, v152
	v_max_f32_e32 v153, 0x1e3ce508, v153
	v_max_f32_e32 v154, 0x1e3ce508, v154
	v_max_f32_e32 v155, 0x1e3ce508, v155
	v_cvt_pk_bf16_f32 v132, v148, v149
	v_cvt_pk_bf16_f32 v133, v150, v151
	v_cvt_pk_bf16_f32 v134, v152, v153
	v_cvt_pk_bf16_f32 v135, v154, v155
	flat_store_dwordx4 v[130:131], v[132:135]
	v_lshl_add_u64 v[130:131], v[130:131], 0, s[6:7]
	v_pk_mul_f32 v[148:149], v[30:31], s[0:1] op_sel_hi:[1,0]
	v_pk_mul_f32 v[150:151], v[32:33], s[0:1] op_sel_hi:[1,0]
	v_pk_mul_f32 v[152:153], v[26:27], s[0:1] op_sel_hi:[1,0]
	v_pk_mul_f32 v[154:155], v[28:29], s[0:1] op_sel_hi:[1,0]
	v_exp_f32_e32 v148, v148
	v_exp_f32_e32 v149, v149
	v_exp_f32_e32 v150, v150
	v_exp_f32_e32 v151, v151
	v_exp_f32_e32 v152, v152
	v_exp_f32_e32 v153, v153
	v_exp_f32_e32 v154, v154
	v_exp_f32_e32 v155, v155
	v_pk_add_f32 v[148:149], v[148:149], s[0:1] op_sel:[0,1] op_sel_hi:[1,1]
	v_pk_add_f32 v[150:151], v[150:151], s[0:1] op_sel:[0,1] op_sel_hi:[1,1]
	v_pk_add_f32 v[152:153], v[152:153], s[0:1] op_sel:[0,1] op_sel_hi:[1,1]
	v_pk_add_f32 v[154:155], v[154:155], s[0:1] op_sel:[0,1] op_sel_hi:[1,1]
	v_rcp_f32_e32 v148, v148
	v_rcp_f32_e32 v149, v149
	v_rcp_f32_e32 v150, v150
	v_rcp_f32_e32 v151, v151
	v_rcp_f32_e32 v152, v152
	v_rcp_f32_e32 v153, v153
	v_rcp_f32_e32 v154, v154
	v_rcp_f32_e32 v155, v155
	v_max_f32_e32 v148, 0x1e3ce508, v148
	v_max_f32_e32 v149, 0x1e3ce508, v149
	v_max_f32_e32 v150, 0x1e3ce508, v150
	v_max_f32_e32 v151, 0x1e3ce508, v151
	v_max_f32_e32 v152, 0x1e3ce508, v152
	v_max_f32_e32 v153, 0x1e3ce508, v153
	v_max_f32_e32 v154, 0x1e3ce508, v154
	v_max_f32_e32 v155, 0x1e3ce508, v155
	v_cvt_pk_bf16_f32 v132, v148, v149
	v_cvt_pk_bf16_f32 v133, v150, v151
	v_cvt_pk_bf16_f32 v134, v152, v153
	v_cvt_pk_bf16_f32 v135, v154, v155
	flat_store_dwordx4 v[130:131], v[132:135]
	v_lshl_add_u64 v[130:131], v[130:131], 0, s[6:7]
	v_pk_mul_f32 v[148:149], v[54:55], s[0:1] op_sel_hi:[1,0]
	v_pk_mul_f32 v[150:151], v[56:57], s[0:1] op_sel_hi:[1,0]
	v_pk_mul_f32 v[152:153], v[50:51], s[0:1] op_sel_hi:[1,0]
	v_pk_mul_f32 v[154:155], v[52:53], s[0:1] op_sel_hi:[1,0]
	v_exp_f32_e32 v148, v148
	v_exp_f32_e32 v149, v149
	v_exp_f32_e32 v150, v150
	v_exp_f32_e32 v151, v151
	v_exp_f32_e32 v152, v152
	v_exp_f32_e32 v153, v153
	v_exp_f32_e32 v154, v154
	v_exp_f32_e32 v155, v155
	v_pk_add_f32 v[148:149], v[148:149], s[0:1] op_sel:[0,1] op_sel_hi:[1,1]
	v_pk_add_f32 v[150:151], v[150:151], s[0:1] op_sel:[0,1] op_sel_hi:[1,1]
	v_pk_add_f32 v[152:153], v[152:153], s[0:1] op_sel:[0,1] op_sel_hi:[1,1]
	v_pk_add_f32 v[154:155], v[154:155], s[0:1] op_sel:[0,1] op_sel_hi:[1,1]
	v_rcp_f32_e32 v148, v148
	v_rcp_f32_e32 v149, v149
	v_rcp_f32_e32 v150, v150
	v_rcp_f32_e32 v151, v151
	v_rcp_f32_e32 v152, v152
	v_rcp_f32_e32 v153, v153
	v_rcp_f32_e32 v154, v154
	v_rcp_f32_e32 v155, v155
	v_max_f32_e32 v148, 0x1e3ce508, v148
	v_max_f32_e32 v149, 0x1e3ce508, v149
	v_max_f32_e32 v150, 0x1e3ce508, v150
	v_max_f32_e32 v151, 0x1e3ce508, v151
	v_max_f32_e32 v152, 0x1e3ce508, v152
	v_max_f32_e32 v153, 0x1e3ce508, v153
	v_max_f32_e32 v154, 0x1e3ce508, v154
	v_max_f32_e32 v155, 0x1e3ce508, v155
	v_cvt_pk_bf16_f32 v132, v148, v149
	v_cvt_pk_bf16_f32 v133, v150, v151
	v_cvt_pk_bf16_f32 v134, v152, v153
	v_cvt_pk_bf16_f32 v135, v154, v155
	flat_store_dwordx4 v[130:131], v[132:135]
	v_lshl_add_u64 v[130:131], v[130:131], 0, s[6:7]
	v_pk_mul_f32 v[148:149], v[22:23], s[0:1] op_sel_hi:[1,0]
	v_pk_mul_f32 v[150:151], v[24:25], s[0:1] op_sel_hi:[1,0]
	v_pk_mul_f32 v[152:153], v[18:19], s[0:1] op_sel_hi:[1,0]
	v_pk_mul_f32 v[154:155], v[20:21], s[0:1] op_sel_hi:[1,0]
	v_exp_f32_e32 v148, v148
	v_exp_f32_e32 v149, v149
	v_exp_f32_e32 v150, v150
	v_exp_f32_e32 v151, v151
	v_exp_f32_e32 v152, v152
	v_exp_f32_e32 v153, v153
	v_exp_f32_e32 v154, v154
	v_exp_f32_e32 v155, v155
	v_pk_add_f32 v[148:149], v[148:149], s[0:1] op_sel:[0,1] op_sel_hi:[1,1]
	v_pk_add_f32 v[150:151], v[150:151], s[0:1] op_sel:[0,1] op_sel_hi:[1,1]
	v_pk_add_f32 v[152:153], v[152:153], s[0:1] op_sel:[0,1] op_sel_hi:[1,1]
	v_pk_add_f32 v[154:155], v[154:155], s[0:1] op_sel:[0,1] op_sel_hi:[1,1]
	v_rcp_f32_e32 v148, v148
	v_rcp_f32_e32 v149, v149
	v_rcp_f32_e32 v150, v150
	v_rcp_f32_e32 v151, v151
	v_rcp_f32_e32 v152, v152
	v_rcp_f32_e32 v153, v153
	v_rcp_f32_e32 v154, v154
	v_rcp_f32_e32 v155, v155
	v_max_f32_e32 v148, 0x1e3ce508, v148
	v_max_f32_e32 v149, 0x1e3ce508, v149
	v_max_f32_e32 v150, 0x1e3ce508, v150
	v_max_f32_e32 v151, 0x1e3ce508, v151
	v_max_f32_e32 v152, 0x1e3ce508, v152
	v_max_f32_e32 v153, 0x1e3ce508, v153
	v_max_f32_e32 v154, 0x1e3ce508, v154
	v_max_f32_e32 v155, 0x1e3ce508, v155
	v_cvt_pk_bf16_f32 v132, v148, v149
	v_cvt_pk_bf16_f32 v133, v150, v151
	v_cvt_pk_bf16_f32 v134, v152, v153
	v_cvt_pk_bf16_f32 v135, v154, v155
	flat_store_dwordx4 v[130:131], v[132:135]
	v_lshl_add_u64 v[130:131], v[130:131], 0, s[6:7]
	v_pk_mul_f32 v[148:149], v[46:47], s[0:1] op_sel_hi:[1,0]
	v_pk_mul_f32 v[150:151], v[48:49], s[0:1] op_sel_hi:[1,0]
	v_pk_mul_f32 v[152:153], v[42:43], s[0:1] op_sel_hi:[1,0]
	v_pk_mul_f32 v[154:155], v[44:45], s[0:1] op_sel_hi:[1,0]
	v_exp_f32_e32 v148, v148
	v_exp_f32_e32 v149, v149
	v_exp_f32_e32 v150, v150
	v_exp_f32_e32 v151, v151
	v_exp_f32_e32 v152, v152
	v_exp_f32_e32 v153, v153
	v_exp_f32_e32 v154, v154
	v_exp_f32_e32 v155, v155
	v_pk_add_f32 v[148:149], v[148:149], s[0:1] op_sel:[0,1] op_sel_hi:[1,1]
	v_pk_add_f32 v[150:151], v[150:151], s[0:1] op_sel:[0,1] op_sel_hi:[1,1]
	v_pk_add_f32 v[152:153], v[152:153], s[0:1] op_sel:[0,1] op_sel_hi:[1,1]
	v_pk_add_f32 v[154:155], v[154:155], s[0:1] op_sel:[0,1] op_sel_hi:[1,1]
	v_rcp_f32_e32 v148, v148
	v_rcp_f32_e32 v149, v149
	v_rcp_f32_e32 v150, v150
	v_rcp_f32_e32 v151, v151
	v_rcp_f32_e32 v152, v152
	v_rcp_f32_e32 v153, v153
	v_rcp_f32_e32 v154, v154
	v_rcp_f32_e32 v155, v155
	v_max_f32_e32 v148, 0x1e3ce508, v148
	v_max_f32_e32 v149, 0x1e3ce508, v149
	v_max_f32_e32 v150, 0x1e3ce508, v150
	v_max_f32_e32 v151, 0x1e3ce508, v151
	v_max_f32_e32 v152, 0x1e3ce508, v152
	v_max_f32_e32 v153, 0x1e3ce508, v153
	v_max_f32_e32 v154, 0x1e3ce508, v154
	v_max_f32_e32 v155, 0x1e3ce508, v155
	v_cvt_pk_bf16_f32 v132, v148, v149
	v_cvt_pk_bf16_f32 v133, v150, v151
	v_cvt_pk_bf16_f32 v134, v152, v153
	v_cvt_pk_bf16_f32 v135, v154, v155
	flat_store_dwordx4 v[130:131], v[132:135]
	v_lshl_add_u64 v[130:131], v[130:131], 0, s[6:7]
	v_pk_mul_f32 v[148:149], v[14:15], s[0:1] op_sel_hi:[1,0]
	v_pk_mul_f32 v[150:151], v[16:17], s[0:1] op_sel_hi:[1,0]
	v_pk_mul_f32 v[152:153], v[10:11], s[0:1] op_sel_hi:[1,0]
	v_pk_mul_f32 v[154:155], v[12:13], s[0:1] op_sel_hi:[1,0]
	v_exp_f32_e32 v148, v148
	v_exp_f32_e32 v149, v149
	v_exp_f32_e32 v150, v150
	v_exp_f32_e32 v151, v151
	v_exp_f32_e32 v152, v152
	v_exp_f32_e32 v153, v153
	v_exp_f32_e32 v154, v154
	v_exp_f32_e32 v155, v155
	v_pk_add_f32 v[148:149], v[148:149], s[0:1] op_sel:[0,1] op_sel_hi:[1,1]
	v_pk_add_f32 v[150:151], v[150:151], s[0:1] op_sel:[0,1] op_sel_hi:[1,1]
	v_pk_add_f32 v[152:153], v[152:153], s[0:1] op_sel:[0,1] op_sel_hi:[1,1]
	v_pk_add_f32 v[154:155], v[154:155], s[0:1] op_sel:[0,1] op_sel_hi:[1,1]
	v_rcp_f32_e32 v148, v148
	v_rcp_f32_e32 v149, v149
	v_rcp_f32_e32 v150, v150
	v_rcp_f32_e32 v151, v151
	v_rcp_f32_e32 v152, v152
	v_rcp_f32_e32 v153, v153
	v_rcp_f32_e32 v154, v154
	v_rcp_f32_e32 v155, v155
	v_max_f32_e32 v148, 0x1e3ce508, v148
	v_max_f32_e32 v149, 0x1e3ce508, v149
	v_max_f32_e32 v150, 0x1e3ce508, v150
	v_max_f32_e32 v151, 0x1e3ce508, v151
	v_max_f32_e32 v152, 0x1e3ce508, v152
	v_max_f32_e32 v153, 0x1e3ce508, v153
	v_max_f32_e32 v154, 0x1e3ce508, v154
	v_max_f32_e32 v155, 0x1e3ce508, v155
	v_cvt_pk_bf16_f32 v132, v148, v149
	v_cvt_pk_bf16_f32 v133, v150, v151
	v_cvt_pk_bf16_f32 v134, v152, v153
	v_cvt_pk_bf16_f32 v135, v154, v155
	flat_store_dwordx4 v[130:131], v[132:135]
	v_lshl_add_u64 v[130:131], v[130:131], 0, s[6:7]
	v_pk_mul_f32 v[148:149], v[38:39], s[0:1] op_sel_hi:[1,0]
	v_pk_mul_f32 v[150:151], v[40:41], s[0:1] op_sel_hi:[1,0]
	v_pk_mul_f32 v[152:153], v[34:35], s[0:1] op_sel_hi:[1,0]
	v_pk_mul_f32 v[154:155], v[36:37], s[0:1] op_sel_hi:[1,0]
	v_exp_f32_e32 v148, v148
	v_exp_f32_e32 v149, v149
	v_exp_f32_e32 v150, v150
	v_exp_f32_e32 v151, v151
	v_exp_f32_e32 v152, v152
	v_exp_f32_e32 v153, v153
	v_exp_f32_e32 v154, v154
	v_exp_f32_e32 v155, v155
	v_pk_add_f32 v[148:149], v[148:149], s[0:1] op_sel:[0,1] op_sel_hi:[1,1]
	v_pk_add_f32 v[150:151], v[150:151], s[0:1] op_sel:[0,1] op_sel_hi:[1,1]
	v_pk_add_f32 v[152:153], v[152:153], s[0:1] op_sel:[0,1] op_sel_hi:[1,1]
	v_pk_add_f32 v[154:155], v[154:155], s[0:1] op_sel:[0,1] op_sel_hi:[1,1]
	v_rcp_f32_e32 v148, v148
	v_rcp_f32_e32 v149, v149
	v_rcp_f32_e32 v150, v150
	v_rcp_f32_e32 v151, v151
	v_rcp_f32_e32 v152, v152
	v_rcp_f32_e32 v153, v153
	v_rcp_f32_e32 v154, v154
	v_rcp_f32_e32 v155, v155
	v_max_f32_e32 v148, 0x1e3ce508, v148
	v_max_f32_e32 v149, 0x1e3ce508, v149
	v_max_f32_e32 v150, 0x1e3ce508, v150
	v_max_f32_e32 v151, 0x1e3ce508, v151
	v_max_f32_e32 v152, 0x1e3ce508, v152
	v_max_f32_e32 v153, 0x1e3ce508, v153
	v_max_f32_e32 v154, 0x1e3ce508, v154
	v_max_f32_e32 v155, 0x1e3ce508, v155
	v_cvt_pk_bf16_f32 v132, v148, v149
	v_cvt_pk_bf16_f32 v133, v150, v151
	v_cvt_pk_bf16_f32 v134, v152, v153
	v_cvt_pk_bf16_f32 v135, v154, v155
	flat_store_dwordx4 v[130:131], v[132:135]
	v_lshl_add_u64 v[130:131], v[130:131], 0, s[6:7]
	v_pk_mul_f32 v[148:149], v[6:7], s[0:1] op_sel_hi:[1,0]
	v_pk_mul_f32 v[150:151], v[8:9], s[0:1] op_sel_hi:[1,0]
	v_pk_mul_f32 v[152:153], v[2:3], s[0:1] op_sel_hi:[1,0]
	v_pk_mul_f32 v[154:155], v[4:5], s[0:1] op_sel_hi:[1,0]
	v_exp_f32_e32 v148, v148
	v_exp_f32_e32 v149, v149
	v_exp_f32_e32 v150, v150
	v_exp_f32_e32 v151, v151
	v_exp_f32_e32 v152, v152
	v_exp_f32_e32 v153, v153
	v_exp_f32_e32 v154, v154
	v_exp_f32_e32 v155, v155
	v_pk_add_f32 v[148:149], v[148:149], s[0:1] op_sel:[0,1] op_sel_hi:[1,1]
	v_pk_add_f32 v[150:151], v[150:151], s[0:1] op_sel:[0,1] op_sel_hi:[1,1]
	v_pk_add_f32 v[152:153], v[152:153], s[0:1] op_sel:[0,1] op_sel_hi:[1,1]
	v_pk_add_f32 v[154:155], v[154:155], s[0:1] op_sel:[0,1] op_sel_hi:[1,1]
	v_rcp_f32_e32 v148, v148
	v_rcp_f32_e32 v149, v149
	v_rcp_f32_e32 v150, v150
	v_rcp_f32_e32 v151, v151
	v_rcp_f32_e32 v152, v152
	v_rcp_f32_e32 v153, v153
	v_rcp_f32_e32 v154, v154
	v_rcp_f32_e32 v155, v155
	v_max_f32_e32 v148, 0x1e3ce508, v148
	v_max_f32_e32 v149, 0x1e3ce508, v149
	v_max_f32_e32 v150, 0x1e3ce508, v150
	v_max_f32_e32 v151, 0x1e3ce508, v151
	v_max_f32_e32 v152, 0x1e3ce508, v152
	v_max_f32_e32 v153, 0x1e3ce508, v153
	v_max_f32_e32 v154, 0x1e3ce508, v154
	v_max_f32_e32 v155, 0x1e3ce508, v155
	v_cvt_pk_bf16_f32 v132, v148, v149
	v_cvt_pk_bf16_f32 v133, v150, v151
	v_cvt_pk_bf16_f32 v134, v152, v153
	v_cvt_pk_bf16_f32 v135, v154, v155
	flat_store_dwordx4 v[130:131], v[132:135]
	s_mov_b64 s[0:1], 0
